# v13 + K-loop LDS-DMA uses SGPR-base addressing (16 v_lshl_add_u64 per iteration removed, +0x80 offsets hoisted), s_nop after every m0 write
# speedup vs baseline: 1.0041x; 1.0041x over previous
.LBB0_251:
	s_ashr_i32 s47, s46, 31
	s_lshl_b64 s[48:49], s[46:47], 21
	s_add_u32 s48, s78, s48
	s_addc_u32 s49, s77, s49
	s_and_b64 s[50:51], s[38:39], exec
	s_cselect_b32 s47, s49, s55
	s_cselect_b32 s66, s48, s54
	s_ashr_i32 s45, s44, 31
	s_lshl_b64 s[50:51], s[44:45], 21
	s_add_u32 s50, s80, s50
	s_addc_u32 s51, s79, s51
	s_and_b64 s[64:65], s[38:39], exec
	s_cselect_b32 s45, s51, s63
	s_cselect_b32 vcc_lo, s50, s62
	s_add_u32 s54, s54, 0x100080
	s_addc_u32 s55, s55, 0
	s_add_u32 vcc_hi, s62, 0x100
	v_mov_b32_e32 v2, 0
	s_addc_u32 s61, s63, 0
	s_mov_b32 s94, -2
	v_mov_b32_e32 v3, v2
	v_mov_b32_e32 v4, v2
	v_mov_b32_e32 v5, v2
	v_mov_b32_e32 v6, v2
	v_mov_b32_e32 v7, v2
	v_mov_b32_e32 v8, v2
	v_mov_b32_e32 v9, v2
	v_mov_b32_e32 v14, v2
	v_mov_b32_e32 v15, v2
	v_mov_b32_e32 v16, v2
	v_mov_b32_e32 v17, v2
	v_mov_b32_e32 v22, v2
	v_mov_b32_e32 v23, v2
	v_mov_b32_e32 v24, v2
	v_mov_b32_e32 v25, v2
	v_mov_b32_e32 v30, v2
	v_mov_b32_e32 v31, v2
	v_mov_b32_e32 v32, v2
	v_mov_b32_e32 v33, v2
	v_mov_b32_e32 v38, v2
	v_mov_b32_e32 v39, v2
	v_mov_b32_e32 v40, v2
	v_mov_b32_e32 v41, v2
	v_mov_b32_e32 v46, v2
	v_mov_b32_e32 v47, v2
	v_mov_b32_e32 v48, v2
	v_mov_b32_e32 v49, v2
	v_mov_b32_e32 v54, v2
	v_mov_b32_e32 v55, v2
	v_mov_b32_e32 v56, v2
	v_mov_b32_e32 v57, v2
	v_mov_b32_e32 v10, v2
	v_mov_b32_e32 v11, v2
	v_mov_b32_e32 v12, v2
	v_mov_b32_e32 v13, v2
	v_mov_b32_e32 v18, v2
	v_mov_b32_e32 v19, v2
	v_mov_b32_e32 v20, v2
	v_mov_b32_e32 v21, v2
	v_mov_b32_e32 v26, v2
	v_mov_b32_e32 v27, v2
	v_mov_b32_e32 v28, v2
	v_mov_b32_e32 v29, v2
	v_mov_b32_e32 v34, v2
	v_mov_b32_e32 v35, v2
	v_mov_b32_e32 v36, v2
	v_mov_b32_e32 v37, v2
	v_mov_b32_e32 v42, v2
	v_mov_b32_e32 v43, v2
	v_mov_b32_e32 v44, v2
	v_mov_b32_e32 v45, v2
	v_mov_b32_e32 v50, v2
	v_mov_b32_e32 v51, v2
	v_mov_b32_e32 v52, v2
	v_mov_b32_e32 v53, v2
	v_mov_b32_e32 v58, v2
	v_mov_b32_e32 v59, v2
	v_mov_b32_e32 v60, v2
	v_mov_b32_e32 v61, v2
	v_mov_b32_e32 v62, v2
	v_mov_b32_e32 v63, v2
	v_mov_b32_e32 v64, v2
	v_mov_b32_e32 v65, v2
	v_mov_b32_e32 v66, v2
	v_mov_b32_e32 v67, v2
	v_mov_b32_e32 v68, v2
	v_mov_b32_e32 v69, v2
	v_mov_b32_e32 v70, v2
	v_mov_b32_e32 v71, v2
	v_mov_b32_e32 v72, v2
	v_mov_b32_e32 v73, v2
	v_mov_b32_e32 v78, v2
	v_mov_b32_e32 v79, v2
	v_mov_b32_e32 v80, v2
	v_mov_b32_e32 v81, v2
	v_mov_b32_e32 v86, v2
	v_mov_b32_e32 v87, v2
	v_mov_b32_e32 v88, v2
	v_mov_b32_e32 v89, v2
	v_mov_b32_e32 v94, v2
	v_mov_b32_e32 v95, v2
	v_mov_b32_e32 v96, v2
	v_mov_b32_e32 v97, v2
	v_mov_b32_e32 v102, v2
	v_mov_b32_e32 v103, v2
	v_mov_b32_e32 v104, v2
	v_mov_b32_e32 v105, v2
	v_mov_b32_e32 v110, v2
	v_mov_b32_e32 v111, v2
	v_mov_b32_e32 v112, v2
	v_mov_b32_e32 v113, v2
	v_mov_b32_e32 v118, v2
	v_mov_b32_e32 v119, v2
	v_mov_b32_e32 v120, v2
	v_mov_b32_e32 v121, v2
	v_mov_b32_e32 v74, v2
	v_mov_b32_e32 v75, v2
	v_mov_b32_e32 v76, v2
	v_mov_b32_e32 v77, v2
	v_mov_b32_e32 v82, v2
	v_mov_b32_e32 v83, v2
	v_mov_b32_e32 v84, v2
	v_mov_b32_e32 v85, v2
	v_mov_b32_e32 v90, v2
	v_mov_b32_e32 v91, v2
	v_mov_b32_e32 v92, v2
	v_mov_b32_e32 v93, v2
	v_mov_b32_e32 v98, v2
	v_mov_b32_e32 v99, v2
	v_mov_b32_e32 v100, v2
	v_mov_b32_e32 v101, v2
	v_mov_b32_e32 v106, v2
	v_mov_b32_e32 v107, v2
	v_mov_b32_e32 v108, v2
	v_mov_b32_e32 v109, v2
	v_mov_b32_e32 v114, v2
	v_mov_b32_e32 v115, v2
	v_mov_b32_e32 v116, v2
	v_mov_b32_e32 v117, v2
	v_mov_b32_e32 v122, v2
	v_mov_b32_e32 v123, v2
	v_mov_b32_e32 v124, v2
	v_mov_b32_e32 v125, v2
	v_mov_b32_e32 v126, v2
	v_mov_b32_e32 v127, v2
	v_mov_b32_e32 v128, v2
	v_mov_b32_e32 v129, v2
	v_add_u32_e32 v143, 0x80, v130
	v_add_u32_e32 v188, 0x80, v132
	v_add_u32_e32 v189, 0x80, v134
	v_add_u32_e32 v234, 0x80, v190
.LBB0_252:
	s_add_u32 s12, s54, 0xfff00080
	s_addc_u32 s13, s55, -1
	s_add_i32 s95, 0, 0x10000
	s_cmp_eq_u32 s94, 60
	s_cselect_b32 s65, s47, s13
	s_cselect_b32 s64, s66, s12
	s_cselect_b32 s63, s45, s61
	s_cselect_b32 s62, vcc_lo, vcc_hi
	s_add_i32 s56, 0, 0x14000
	s_add_i32 m0, s53, 0xc000
	s_nop 0
	global_load_lds_dwordx4 v136, s[54:55]
	s_add_i32 m0, s53, 0xe000
	s_nop 0
	global_load_lds_dwordx4 v138, s[54:55]
	v_add_u32_e32 v142, s95, v144
	ds_read_b128 v[148:151], v142
	ds_read_b128 v[152:155], v142 offset:1024
	ds_read_b128 v[156:159], v142 offset:2048
	ds_read_b128 v[160:163], v142 offset:3072
	v_add_u32_e32 v142, s56, v144
	ds_read_b128 v[164:167], v142
	ds_read_b128 v[168:171], v142 offset:1024
	ds_read_b128 v[172:175], v142 offset:2048
	ds_read_b128 v[176:179], v142 offset:3072
	ds_read_b128 v[180:183], v146
	ds_read_b128 v[184:187], v146 offset:1024
	ds_read_b128 v[210:213], v146 offset:2048
	ds_read_b128 v[214:217], v146 offset:3072
	ds_read_b128 v[218:221], v146 offset:4096
	ds_read_b128 v[222:225], v146 offset:5120
	ds_read_b128 v[226:229], v146 offset:6144
	ds_read_b128 v[230:233], v146 offset:7168
	s_waitcnt vmcnt(8)
	s_waitcnt lgkmcnt(0)
	s_barrier
	s_setprio 1
	s_waitcnt lgkmcnt(0)
	v_mfma_f32_16x16x32_bf16 v[126:129], v[148:151], v[180:183], v[126:129]
	v_mfma_f32_16x16x32_bf16 v[126:129], v[152:155], v[184:187], v[126:129]
	v_mfma_f32_16x16x32_bf16 v[114:117], v[152:155], v[214:217], v[114:117]
	v_mfma_f32_16x16x32_bf16 v[114:117], v[148:151], v[210:213], v[114:117]
	v_mfma_f32_16x16x32_bf16 v[98:101], v[148:151], v[218:221], v[98:101]
	v_mfma_f32_16x16x32_bf16 v[98:101], v[152:155], v[222:225], v[98:101]
	v_mfma_f32_16x16x32_bf16 v[82:85], v[152:155], v[230:233], v[82:85]
	v_mfma_f32_16x16x32_bf16 v[82:85], v[148:151], v[226:229], v[82:85]
	v_mfma_f32_16x16x32_bf16 v[74:77], v[156:159], v[226:229], v[74:77]
	v_mfma_f32_16x16x32_bf16 v[74:77], v[160:163], v[230:233], v[74:77]
	v_mfma_f32_16x16x32_bf16 v[90:93], v[160:163], v[222:225], v[90:93]
	v_mfma_f32_16x16x32_bf16 v[90:93], v[156:159], v[218:221], v[90:93]
	v_mfma_f32_16x16x32_bf16 v[106:109], v[156:159], v[210:213], v[106:109]
	v_mfma_f32_16x16x32_bf16 v[106:109], v[160:163], v[214:217], v[106:109]
	v_mfma_f32_16x16x32_bf16 v[122:125], v[160:163], v[184:187], v[122:125]
	v_mfma_f32_16x16x32_bf16 v[122:125], v[156:159], v[180:183], v[122:125]
	v_mfma_f32_16x16x32_bf16 v[110:113], v[172:175], v[180:183], v[110:113]
	v_mfma_f32_16x16x32_bf16 v[110:113], v[176:179], v[184:187], v[110:113]
	v_mfma_f32_16x16x32_bf16 v[94:97], v[176:179], v[214:217], v[94:97]
	v_mfma_f32_16x16x32_bf16 v[94:97], v[172:175], v[210:213], v[94:97]
	v_mfma_f32_16x16x32_bf16 v[78:81], v[172:175], v[218:221], v[78:81]
	v_mfma_f32_16x16x32_bf16 v[78:81], v[176:179], v[222:225], v[78:81]
	v_mfma_f32_16x16x32_bf16 v[66:69], v[176:179], v[230:233], v[66:69]
	v_mfma_f32_16x16x32_bf16 v[66:69], v[172:175], v[226:229], v[66:69]
	v_mfma_f32_16x16x32_bf16 v[70:73], v[164:167], v[226:229], v[70:73]
	v_mfma_f32_16x16x32_bf16 v[70:73], v[168:171], v[230:233], v[70:73]
	v_mfma_f32_16x16x32_bf16 v[86:89], v[168:171], v[222:225], v[86:89]
	v_mfma_f32_16x16x32_bf16 v[86:89], v[164:167], v[218:221], v[86:89]
	v_mfma_f32_16x16x32_bf16 v[102:105], v[164:167], v[210:213], v[102:105]
	v_mfma_f32_16x16x32_bf16 v[102:105], v[168:171], v[214:217], v[102:105]
	v_mfma_f32_16x16x32_bf16 v[118:121], v[168:171], v[184:187], v[118:121]
	v_mfma_f32_16x16x32_bf16 v[118:121], v[164:167], v[180:183], v[118:121]
	s_setprio 0
	s_barrier
	s_add_i32 s12, s95, s82
	s_mov_b32 m0, s12
	s_nop 0
	global_load_lds_dwordx4 v190, s[62:63]
	s_add_i32 m0, s12, 0x2000
	s_add_u32 s12, s62, 0x100000
	s_addc_u32 s13, s63, 0
	s_add_i32 s56, s56, s82
	global_load_lds_dwordx4 v134, s[62:63]
	s_mov_b32 m0, s56
	s_nop 0
	global_load_lds_dwordx4 v190, s[12:13]
	s_add_i32 m0, s56, 0x2000
	s_nop 0
	global_load_lds_dwordx4 v134, s[12:13]
	s_mov_b32 m0, s53
	s_nop 0
	global_load_lds_dwordx4 v130, s[64:65]
	s_mov_b32 m0, s84
	s_nop 0
	global_load_lds_dwordx4 v132, s[64:65]
	ds_read_b128 v[180:183], v146 offset:16384
	ds_read_b128 v[184:187], v146 offset:17408
	ds_read_b128 v[210:213], v146 offset:18432
	ds_read_b128 v[214:217], v146 offset:19456
	ds_read_b128 v[218:221], v146 offset:20480
	ds_read_b128 v[222:225], v146 offset:21504
	ds_read_b128 v[226:229], v146 offset:22528
	ds_read_b128 v[230:233], v146 offset:23552
	s_waitcnt vmcnt(8)
	s_waitcnt lgkmcnt(0)
	s_barrier
	s_setprio 1
	s_waitcnt lgkmcnt(0)
	v_mfma_f32_16x16x32_bf16 v[62:65], v[148:151], v[180:183], v[62:65]
	v_mfma_f32_16x16x32_bf16 v[62:65], v[152:155], v[184:187], v[62:65]
	v_mfma_f32_16x16x32_bf16 v[50:53], v[152:155], v[214:217], v[50:53]
	v_mfma_f32_16x16x32_bf16 v[50:53], v[148:151], v[210:213], v[50:53]
	v_mfma_f32_16x16x32_bf16 v[34:37], v[148:151], v[218:221], v[34:37]
	v_mfma_f32_16x16x32_bf16 v[34:37], v[152:155], v[222:225], v[34:37]
	v_mfma_f32_16x16x32_bf16 v[18:21], v[152:155], v[230:233], v[18:21]
	v_mfma_f32_16x16x32_bf16 v[18:21], v[148:151], v[226:229], v[18:21]
	v_mfma_f32_16x16x32_bf16 v[10:13], v[156:159], v[226:229], v[10:13]
	v_mfma_f32_16x16x32_bf16 v[10:13], v[160:163], v[230:233], v[10:13]
	v_mfma_f32_16x16x32_bf16 v[26:29], v[160:163], v[222:225], v[26:29]
	v_mfma_f32_16x16x32_bf16 v[26:29], v[156:159], v[218:221], v[26:29]
	v_mfma_f32_16x16x32_bf16 v[42:45], v[156:159], v[210:213], v[42:45]
	v_mfma_f32_16x16x32_bf16 v[42:45], v[160:163], v[214:217], v[42:45]
	v_mfma_f32_16x16x32_bf16 v[58:61], v[160:163], v[184:187], v[58:61]
	v_mfma_f32_16x16x32_bf16 v[58:61], v[156:159], v[180:183], v[58:61]
	v_mfma_f32_16x16x32_bf16 v[46:49], v[172:175], v[180:183], v[46:49]
	v_mfma_f32_16x16x32_bf16 v[46:49], v[176:179], v[184:187], v[46:49]
	v_mfma_f32_16x16x32_bf16 v[30:33], v[176:179], v[214:217], v[30:33]
	v_mfma_f32_16x16x32_bf16 v[30:33], v[172:175], v[210:213], v[30:33]
	v_mfma_f32_16x16x32_bf16 v[14:17], v[172:175], v[218:221], v[14:17]
	v_mfma_f32_16x16x32_bf16 v[14:17], v[176:179], v[222:225], v[14:17]
	v_mfma_f32_16x16x32_bf16 v[2:5], v[176:179], v[230:233], v[2:5]
	v_mfma_f32_16x16x32_bf16 v[2:5], v[172:175], v[226:229], v[2:5]
	v_mfma_f32_16x16x32_bf16 v[6:9], v[164:167], v[226:229], v[6:9]
	v_mfma_f32_16x16x32_bf16 v[6:9], v[168:171], v[230:233], v[6:9]
	v_mfma_f32_16x16x32_bf16 v[22:25], v[168:171], v[222:225], v[22:25]
	v_mfma_f32_16x16x32_bf16 v[22:25], v[164:167], v[218:221], v[22:25]
	v_mfma_f32_16x16x32_bf16 v[38:41], v[164:167], v[210:213], v[38:41]
	v_mfma_f32_16x16x32_bf16 v[38:41], v[168:171], v[214:217], v[38:41]
	v_mfma_f32_16x16x32_bf16 v[54:57], v[168:171], v[184:187], v[54:57]
	v_mfma_f32_16x16x32_bf16 v[54:57], v[164:167], v[180:183], v[54:57]
	s_setprio 0
	s_barrier
	s_add_i32 s56, 0, 0x18000
	s_add_i32 s95, 0, 0x1c000
	s_add_u32 s12, s64, 0x100000
	s_addc_u32 s13, s65, 0
	s_mov_b32 m0, s85
	s_nop 0
	global_load_lds_dwordx4 v130, s[12:13]
	s_mov_b32 m0, s86
	s_nop 0
	global_load_lds_dwordx4 v132, s[12:13]
	v_add_u32_e32 v147, s56, v144
	ds_read_b128 v[148:151], v147
	ds_read_b128 v[152:155], v147 offset:1024
	ds_read_b128 v[156:159], v147 offset:2048
	ds_read_b128 v[160:163], v147 offset:3072
	v_add_u32_e32 v147, s95, v144
	ds_read_b128 v[164:167], v147
	ds_read_b128 v[168:171], v147 offset:1024
	ds_read_b128 v[172:175], v147 offset:2048
	ds_read_b128 v[176:179], v147 offset:3072
	ds_read_b128 v[180:183], v146 offset:32768
	ds_read_b128 v[184:187], v146 offset:33792
	ds_read_b128 v[210:213], v146 offset:34816
	ds_read_b128 v[214:217], v146 offset:35840
	ds_read_b128 v[218:221], v146 offset:36864
	ds_read_b128 v[222:225], v146 offset:37888
	ds_read_b128 v[226:229], v146 offset:38912
	ds_read_b128 v[230:233], v146 offset:39936
	s_waitcnt vmcnt(8)
	s_waitcnt lgkmcnt(0)
	s_barrier
	s_setprio 1
	s_waitcnt lgkmcnt(0)
	v_mfma_f32_16x16x32_bf16 v[126:129], v[148:151], v[180:183], v[126:129]
	v_mfma_f32_16x16x32_bf16 v[126:129], v[152:155], v[184:187], v[126:129]
	v_mfma_f32_16x16x32_bf16 v[114:117], v[152:155], v[214:217], v[114:117]
	v_mfma_f32_16x16x32_bf16 v[114:117], v[148:151], v[210:213], v[114:117]
	v_mfma_f32_16x16x32_bf16 v[98:101], v[148:151], v[218:221], v[98:101]
	v_mfma_f32_16x16x32_bf16 v[98:101], v[152:155], v[222:225], v[98:101]
	v_mfma_f32_16x16x32_bf16 v[82:85], v[152:155], v[230:233], v[82:85]
	v_mfma_f32_16x16x32_bf16 v[82:85], v[148:151], v[226:229], v[82:85]
	v_mfma_f32_16x16x32_bf16 v[74:77], v[156:159], v[226:229], v[74:77]
	v_mfma_f32_16x16x32_bf16 v[74:77], v[160:163], v[230:233], v[74:77]
	v_mfma_f32_16x16x32_bf16 v[90:93], v[160:163], v[222:225], v[90:93]
	v_mfma_f32_16x16x32_bf16 v[90:93], v[156:159], v[218:221], v[90:93]
	v_mfma_f32_16x16x32_bf16 v[106:109], v[156:159], v[210:213], v[106:109]
	v_mfma_f32_16x16x32_bf16 v[106:109], v[160:163], v[214:217], v[106:109]
	v_mfma_f32_16x16x32_bf16 v[122:125], v[160:163], v[184:187], v[122:125]
	v_mfma_f32_16x16x32_bf16 v[122:125], v[156:159], v[180:183], v[122:125]
	v_mfma_f32_16x16x32_bf16 v[110:113], v[172:175], v[180:183], v[110:113]
	v_mfma_f32_16x16x32_bf16 v[110:113], v[176:179], v[184:187], v[110:113]
	v_mfma_f32_16x16x32_bf16 v[94:97], v[176:179], v[214:217], v[94:97]
	v_mfma_f32_16x16x32_bf16 v[94:97], v[172:175], v[210:213], v[94:97]
	v_mfma_f32_16x16x32_bf16 v[78:81], v[172:175], v[218:221], v[78:81]
	v_mfma_f32_16x16x32_bf16 v[78:81], v[176:179], v[222:225], v[78:81]
	v_mfma_f32_16x16x32_bf16 v[66:69], v[176:179], v[230:233], v[66:69]
	v_mfma_f32_16x16x32_bf16 v[66:69], v[172:175], v[226:229], v[66:69]
	v_mfma_f32_16x16x32_bf16 v[70:73], v[164:167], v[226:229], v[70:73]
	v_mfma_f32_16x16x32_bf16 v[70:73], v[168:171], v[230:233], v[70:73]
	v_mfma_f32_16x16x32_bf16 v[86:89], v[168:171], v[222:225], v[86:89]
	v_mfma_f32_16x16x32_bf16 v[86:89], v[164:167], v[218:221], v[86:89]
	v_mfma_f32_16x16x32_bf16 v[102:105], v[164:167], v[210:213], v[102:105]
	v_mfma_f32_16x16x32_bf16 v[102:105], v[168:171], v[214:217], v[102:105]
	v_mfma_f32_16x16x32_bf16 v[118:121], v[168:171], v[184:187], v[118:121]
	v_mfma_f32_16x16x32_bf16 v[118:121], v[164:167], v[180:183], v[118:121]
	s_setprio 0
	s_barrier
	s_add_i32 s12, s56, s82
	s_mov_b32 m0, s12
	s_nop 0
	global_load_lds_dwordx4 v234, s[62:63]
	s_add_i32 m0, s12, 0x2000
	s_add_u32 s12, s62, 0x100080
	s_addc_u32 s13, s63, 0
	s_add_i32 s56, s95, s82
	global_load_lds_dwordx4 v189, s[62:63]
	s_mov_b32 m0, s56
	s_nop 0
	global_load_lds_dwordx4 v190, s[12:13]
	s_add_i32 m0, s56, 0x2000
	s_nop 0
	global_load_lds_dwordx4 v134, s[12:13]
	s_mov_b32 m0, s90
	s_nop 0
	global_load_lds_dwordx4 v143, s[64:65]
	s_mov_b32 m0, s97
	s_nop 0
	global_load_lds_dwordx4 v188, s[64:65]
	ds_read_b128 v[180:183], v146 offset:49152
	ds_read_b128 v[184:187], v146 offset:50176
	ds_read_b128 v[210:213], v146 offset:51200
	ds_read_b128 v[214:217], v146 offset:52224
	ds_read_b128 v[218:221], v146 offset:53248
	ds_read_b128 v[222:225], v146 offset:54272
	ds_read_b128 v[226:229], v146 offset:55296
	ds_read_b128 v[230:233], v146 offset:56320
	s_waitcnt vmcnt(8)
	s_waitcnt lgkmcnt(0)
	s_barrier
	s_setprio 1
	s_waitcnt lgkmcnt(0)
	v_mfma_f32_16x16x32_bf16 v[62:65], v[148:151], v[180:183], v[62:65]
	v_mfma_f32_16x16x32_bf16 v[62:65], v[152:155], v[184:187], v[62:65]
	v_mfma_f32_16x16x32_bf16 v[50:53], v[152:155], v[214:217], v[50:53]
	v_mfma_f32_16x16x32_bf16 v[50:53], v[148:151], v[210:213], v[50:53]
	v_mfma_f32_16x16x32_bf16 v[34:37], v[148:151], v[218:221], v[34:37]
	v_mfma_f32_16x16x32_bf16 v[34:37], v[152:155], v[222:225], v[34:37]
	v_mfma_f32_16x16x32_bf16 v[18:21], v[152:155], v[230:233], v[18:21]
	v_mfma_f32_16x16x32_bf16 v[18:21], v[148:151], v[226:229], v[18:21]
	v_mfma_f32_16x16x32_bf16 v[10:13], v[156:159], v[226:229], v[10:13]
	v_mfma_f32_16x16x32_bf16 v[10:13], v[160:163], v[230:233], v[10:13]
	v_mfma_f32_16x16x32_bf16 v[26:29], v[160:163], v[222:225], v[26:29]
	v_mfma_f32_16x16x32_bf16 v[26:29], v[156:159], v[218:221], v[26:29]
	v_mfma_f32_16x16x32_bf16 v[42:45], v[156:159], v[210:213], v[42:45]
	v_mfma_f32_16x16x32_bf16 v[42:45], v[160:163], v[214:217], v[42:45]
	v_mfma_f32_16x16x32_bf16 v[58:61], v[160:163], v[184:187], v[58:61]
	v_mfma_f32_16x16x32_bf16 v[58:61], v[156:159], v[180:183], v[58:61]
	v_mfma_f32_16x16x32_bf16 v[46:49], v[172:175], v[180:183], v[46:49]
	v_mfma_f32_16x16x32_bf16 v[46:49], v[176:179], v[184:187], v[46:49]
	v_mfma_f32_16x16x32_bf16 v[30:33], v[176:179], v[214:217], v[30:33]
	v_mfma_f32_16x16x32_bf16 v[30:33], v[172:175], v[210:213], v[30:33]
	v_mfma_f32_16x16x32_bf16 v[14:17], v[172:175], v[218:221], v[14:17]
	v_mfma_f32_16x16x32_bf16 v[14:17], v[176:179], v[222:225], v[14:17]
	v_mfma_f32_16x16x32_bf16 v[2:5], v[176:179], v[230:233], v[2:5]
	v_mfma_f32_16x16x32_bf16 v[2:5], v[172:175], v[226:229], v[2:5]
	v_mfma_f32_16x16x32_bf16 v[6:9], v[164:167], v[226:229], v[6:9]
	v_mfma_f32_16x16x32_bf16 v[6:9], v[168:171], v[230:233], v[6:9]
	v_mfma_f32_16x16x32_bf16 v[22:25], v[168:171], v[222:225], v[22:25]
	v_mfma_f32_16x16x32_bf16 v[22:25], v[164:167], v[218:221], v[22:25]
	v_mfma_f32_16x16x32_bf16 v[38:41], v[164:167], v[210:213], v[38:41]
	v_mfma_f32_16x16x32_bf16 v[38:41], v[168:171], v[214:217], v[38:41]
	v_mfma_f32_16x16x32_bf16 v[54:57], v[168:171], v[184:187], v[54:57]
	v_mfma_f32_16x16x32_bf16 v[54:57], v[164:167], v[180:183], v[54:57]
	s_setprio 0
	s_barrier
	s_add_i32 s94, s94, 2
	s_add_u32 s54, s54, 0x100
	s_addc_u32 s55, s55, 0
	s_add_u32 vcc_hi, vcc_hi, 0x100
	s_addc_u32 s61, s61, 0
	s_cmp_gt_u32 s94, 61
	s_cbranch_scc0 .LBB0_252
	s_and_b64 vcc, exec, s[42:43]
	s_cbranch_vccz .LBB0_255
	s_barrier

.LBB0_691:
	s_ashr_i32 s47, s46, 31
	s_lshl_b64 s[12:13], s[46:47], 19
	s_add_u32 s48, s29, s12
	s_addc_u32 s49, s33, s13
	s_and_b64 s[12:13], s[38:39], exec
	s_cselect_b32 s47, s49, s41
	s_cselect_b32 s71, s48, s40
	s_ashr_i32 s45, s44, 31
	s_lshl_b64 s[12:13], s[44:45], 19
	s_add_u32 s50, s57, s12
	s_addc_u32 s51, s58, s13
	s_and_b64 s[12:13], s[38:39], exec
	s_cselect_b32 s45, s51, s55
	s_cselect_b32 s72, s50, s54
	s_add_u32 s40, s40, 0x40080
	s_addc_u32 s41, s41, 0
	s_add_u32 s73, s54, 0x100
	v_mov_b32_e32 v2, 0
	s_addc_u32 s61, s55, 0
	s_mov_b32 s74, -2
	v_mov_b32_e32 v3, v2
	v_mov_b32_e32 v4, v2
	v_mov_b32_e32 v5, v2
	v_mov_b32_e32 v6, v2
	v_mov_b32_e32 v7, v2
	v_mov_b32_e32 v8, v2
	v_mov_b32_e32 v9, v2
	v_mov_b32_e32 v14, v2
	v_mov_b32_e32 v15, v2
	v_mov_b32_e32 v16, v2
	v_mov_b32_e32 v17, v2
	v_mov_b32_e32 v22, v2
	v_mov_b32_e32 v23, v2
	v_mov_b32_e32 v24, v2
	v_mov_b32_e32 v25, v2
	v_mov_b32_e32 v30, v2
	v_mov_b32_e32 v31, v2
	v_mov_b32_e32 v32, v2
	v_mov_b32_e32 v33, v2
	v_mov_b32_e32 v38, v2
	v_mov_b32_e32 v39, v2
	v_mov_b32_e32 v40, v2
	v_mov_b32_e32 v41, v2
	v_mov_b32_e32 v46, v2
	v_mov_b32_e32 v47, v2
	v_mov_b32_e32 v48, v2
	v_mov_b32_e32 v49, v2
	v_mov_b32_e32 v54, v2
	v_mov_b32_e32 v55, v2
	v_mov_b32_e32 v56, v2
	v_mov_b32_e32 v57, v2
	v_mov_b32_e32 v10, v2
	v_mov_b32_e32 v11, v2
	v_mov_b32_e32 v12, v2
	v_mov_b32_e32 v13, v2
	v_mov_b32_e32 v18, v2
	v_mov_b32_e32 v19, v2
	v_mov_b32_e32 v20, v2
	v_mov_b32_e32 v21, v2
	v_mov_b32_e32 v26, v2
	v_mov_b32_e32 v27, v2
	v_mov_b32_e32 v28, v2
	v_mov_b32_e32 v29, v2
	v_mov_b32_e32 v34, v2
	v_mov_b32_e32 v35, v2
	v_mov_b32_e32 v36, v2
	v_mov_b32_e32 v37, v2
	v_mov_b32_e32 v42, v2
	v_mov_b32_e32 v43, v2
	v_mov_b32_e32 v44, v2
	v_mov_b32_e32 v45, v2
	v_mov_b32_e32 v50, v2
	v_mov_b32_e32 v51, v2
	v_mov_b32_e32 v52, v2
	v_mov_b32_e32 v53, v2
	v_mov_b32_e32 v58, v2
	v_mov_b32_e32 v59, v2
	v_mov_b32_e32 v60, v2
	v_mov_b32_e32 v61, v2
	v_mov_b32_e32 v62, v2
	v_mov_b32_e32 v63, v2
	v_mov_b32_e32 v64, v2
	v_mov_b32_e32 v65, v2
	v_mov_b32_e32 v66, v2
	v_mov_b32_e32 v67, v2
	v_mov_b32_e32 v68, v2
	v_mov_b32_e32 v69, v2
	v_mov_b32_e32 v70, v2
	v_mov_b32_e32 v71, v2
	v_mov_b32_e32 v72, v2
	v_mov_b32_e32 v73, v2
	v_mov_b32_e32 v78, v2
	v_mov_b32_e32 v79, v2
	v_mov_b32_e32 v80, v2
	v_mov_b32_e32 v81, v2
	v_mov_b32_e32 v86, v2
	v_mov_b32_e32 v87, v2
	v_mov_b32_e32 v88, v2
	v_mov_b32_e32 v89, v2
	v_mov_b32_e32 v94, v2
	v_mov_b32_e32 v95, v2
	v_mov_b32_e32 v96, v2
	v_mov_b32_e32 v97, v2
	v_mov_b32_e32 v102, v2
	v_mov_b32_e32 v103, v2
	v_mov_b32_e32 v104, v2
	v_mov_b32_e32 v105, v2
	v_mov_b32_e32 v110, v2
	v_mov_b32_e32 v111, v2
	v_mov_b32_e32 v112, v2
	v_mov_b32_e32 v113, v2
	v_mov_b32_e32 v118, v2
	v_mov_b32_e32 v119, v2
	v_mov_b32_e32 v120, v2
	v_mov_b32_e32 v121, v2
	v_mov_b32_e32 v74, v2
	v_mov_b32_e32 v75, v2
	v_mov_b32_e32 v76, v2
	v_mov_b32_e32 v77, v2
	v_mov_b32_e32 v82, v2
	v_mov_b32_e32 v83, v2
	v_mov_b32_e32 v84, v2
	v_mov_b32_e32 v85, v2
	v_mov_b32_e32 v90, v2
	v_mov_b32_e32 v91, v2
	v_mov_b32_e32 v92, v2
	v_mov_b32_e32 v93, v2
	v_mov_b32_e32 v98, v2
	v_mov_b32_e32 v99, v2
	v_mov_b32_e32 v100, v2
	v_mov_b32_e32 v101, v2
	v_mov_b32_e32 v106, v2
	v_mov_b32_e32 v107, v2
	v_mov_b32_e32 v108, v2
	v_mov_b32_e32 v109, v2
	v_mov_b32_e32 v114, v2
	v_mov_b32_e32 v115, v2
	v_mov_b32_e32 v116, v2
	v_mov_b32_e32 v117, v2
	v_mov_b32_e32 v122, v2
	v_mov_b32_e32 v123, v2
	v_mov_b32_e32 v124, v2
	v_mov_b32_e32 v125, v2
	v_mov_b32_e32 v126, v2
	v_mov_b32_e32 v127, v2
	v_mov_b32_e32 v128, v2
	v_mov_b32_e32 v129, v2
	v_add_u32_e32 v188, 0x80, v146
	v_add_u32_e32 v189, 0x80, v148
	v_add_u32_e32 v230, 0x80, v150
	v_add_u32_e32 v231, 0x80, v190
.LBB0_692:
	s_add_u32 s12, s40, 0xfffc0080
	s_addc_u32 s13, s41, -1
	s_add_i32 s56, 0, 0x10000
	s_cmp_eq_u32 s74, 12
	s_cselect_b32 s63, s47, s13
	s_cselect_b32 s62, s71, s12
	s_cselect_b32 s55, s45, s61
	s_cselect_b32 s54, s72, s73
	s_add_i32 s75, 0, 0x14000
	s_add_i32 m0, s53, 0xc000
	s_nop 0
	global_load_lds_dwordx4 v152, s[40:41]
	s_add_i32 m0, s53, 0xe000
	s_nop 0
	global_load_lds_dwordx4 v154, s[40:41]
	v_add_u32_e32 v142, s56, v160
	v_add_u32_e32 v163, s75, v160
	ds_read_b128 v[130:133], v142
	ds_read_b128 v[134:137], v142 offset:1024
	ds_read_b128 v[138:141], v142 offset:2048
	ds_read_b128 v[142:145], v142 offset:3072
	ds_read_b128 v[156:159], v163
	ds_read_b128 v[164:167], v163 offset:1024
	ds_read_b128 v[168:171], v163 offset:2048
	ds_read_b128 v[172:175], v163 offset:3072
	ds_read_b128 v[176:179], v162
	ds_read_b128 v[180:183], v162 offset:1024
	ds_read_b128 v[184:187], v162 offset:2048
	ds_read_b128 v[210:213], v162 offset:3072
	ds_read_b128 v[214:217], v162 offset:4096
	ds_read_b128 v[218:221], v162 offset:5120
	ds_read_b128 v[222:225], v162 offset:6144
	ds_read_b128 v[226:229], v162 offset:7168
	s_waitcnt vmcnt(8)
	s_waitcnt lgkmcnt(0)
	s_barrier
	s_setprio 1
	s_waitcnt lgkmcnt(0)
	v_mfma_f32_16x16x32_bf16 v[126:129], v[130:133], v[176:179], v[126:129]
	v_mfma_f32_16x16x32_bf16 v[126:129], v[134:137], v[180:183], v[126:129]
	v_mfma_f32_16x16x32_bf16 v[114:117], v[134:137], v[210:213], v[114:117]
	v_mfma_f32_16x16x32_bf16 v[114:117], v[130:133], v[184:187], v[114:117]
	v_mfma_f32_16x16x32_bf16 v[98:101], v[130:133], v[214:217], v[98:101]
	v_mfma_f32_16x16x32_bf16 v[98:101], v[134:137], v[218:221], v[98:101]
	v_mfma_f32_16x16x32_bf16 v[82:85], v[134:137], v[226:229], v[82:85]
	v_mfma_f32_16x16x32_bf16 v[82:85], v[130:133], v[222:225], v[82:85]
	v_mfma_f32_16x16x32_bf16 v[74:77], v[138:141], v[222:225], v[74:77]
	v_mfma_f32_16x16x32_bf16 v[74:77], v[142:145], v[226:229], v[74:77]
	v_mfma_f32_16x16x32_bf16 v[90:93], v[142:145], v[218:221], v[90:93]
	v_mfma_f32_16x16x32_bf16 v[90:93], v[138:141], v[214:217], v[90:93]
	v_mfma_f32_16x16x32_bf16 v[106:109], v[138:141], v[184:187], v[106:109]
	v_mfma_f32_16x16x32_bf16 v[106:109], v[142:145], v[210:213], v[106:109]
	v_mfma_f32_16x16x32_bf16 v[122:125], v[142:145], v[180:183], v[122:125]
	v_mfma_f32_16x16x32_bf16 v[122:125], v[138:141], v[176:179], v[122:125]
	v_mfma_f32_16x16x32_bf16 v[110:113], v[168:171], v[176:179], v[110:113]
	v_mfma_f32_16x16x32_bf16 v[110:113], v[172:175], v[180:183], v[110:113]
	v_mfma_f32_16x16x32_bf16 v[94:97], v[172:175], v[210:213], v[94:97]
	v_mfma_f32_16x16x32_bf16 v[94:97], v[168:171], v[184:187], v[94:97]
	v_mfma_f32_16x16x32_bf16 v[78:81], v[168:171], v[214:217], v[78:81]
	v_mfma_f32_16x16x32_bf16 v[78:81], v[172:175], v[218:221], v[78:81]
	v_mfma_f32_16x16x32_bf16 v[66:69], v[172:175], v[226:229], v[66:69]
	v_mfma_f32_16x16x32_bf16 v[66:69], v[168:171], v[222:225], v[66:69]
	v_mfma_f32_16x16x32_bf16 v[70:73], v[156:159], v[222:225], v[70:73]
	v_mfma_f32_16x16x32_bf16 v[70:73], v[164:167], v[226:229], v[70:73]
	v_mfma_f32_16x16x32_bf16 v[86:89], v[164:167], v[218:221], v[86:89]
	v_mfma_f32_16x16x32_bf16 v[86:89], v[156:159], v[214:217], v[86:89]
	v_mfma_f32_16x16x32_bf16 v[102:105], v[156:159], v[184:187], v[102:105]
	v_mfma_f32_16x16x32_bf16 v[102:105], v[164:167], v[210:213], v[102:105]
	v_mfma_f32_16x16x32_bf16 v[118:121], v[164:167], v[180:183], v[118:121]
	v_mfma_f32_16x16x32_bf16 v[118:121], v[156:159], v[176:179], v[118:121]
	s_setprio 0
	s_barrier
	s_add_i32 s12, s56, s59
	s_mov_b32 m0, s12
	s_nop 0
	global_load_lds_dwordx4 v190, s[54:55]
	s_add_i32 m0, s12, 0x2000
	s_add_u32 s12, s54, 0x40000
	s_addc_u32 s13, s55, 0
	s_add_i32 s56, s75, s59
	global_load_lds_dwordx4 v150, s[54:55]
	s_mov_b32 m0, s56
	s_nop 0
	global_load_lds_dwordx4 v190, s[12:13]
	s_add_i32 m0, s56, 0x2000
	s_nop 0
	global_load_lds_dwordx4 v150, s[12:13]
	s_mov_b32 m0, s53
	s_nop 0
	global_load_lds_dwordx4 v146, s[62:63]
	s_mov_b32 m0, s60
	s_nop 0
	global_load_lds_dwordx4 v148, s[62:63]
	ds_read_b128 v[176:179], v162 offset:16384
	ds_read_b128 v[180:183], v162 offset:17408
	ds_read_b128 v[184:187], v162 offset:18432
	ds_read_b128 v[210:213], v162 offset:19456
	ds_read_b128 v[214:217], v162 offset:20480
	ds_read_b128 v[218:221], v162 offset:21504
	ds_read_b128 v[222:225], v162 offset:22528
	ds_read_b128 v[226:229], v162 offset:23552
	s_waitcnt vmcnt(8)
	s_waitcnt lgkmcnt(0)
	s_barrier
	s_setprio 1
	s_waitcnt lgkmcnt(0)
	v_mfma_f32_16x16x32_bf16 v[62:65], v[130:133], v[176:179], v[62:65]
	v_mfma_f32_16x16x32_bf16 v[62:65], v[134:137], v[180:183], v[62:65]
	v_mfma_f32_16x16x32_bf16 v[50:53], v[134:137], v[210:213], v[50:53]
	v_mfma_f32_16x16x32_bf16 v[50:53], v[130:133], v[184:187], v[50:53]
	v_mfma_f32_16x16x32_bf16 v[34:37], v[130:133], v[214:217], v[34:37]
	v_mfma_f32_16x16x32_bf16 v[34:37], v[134:137], v[218:221], v[34:37]
	v_mfma_f32_16x16x32_bf16 v[18:21], v[134:137], v[226:229], v[18:21]
	v_mfma_f32_16x16x32_bf16 v[18:21], v[130:133], v[222:225], v[18:21]
	v_mfma_f32_16x16x32_bf16 v[10:13], v[138:141], v[222:225], v[10:13]
	v_mfma_f32_16x16x32_bf16 v[10:13], v[142:145], v[226:229], v[10:13]
	v_mfma_f32_16x16x32_bf16 v[26:29], v[142:145], v[218:221], v[26:29]
	v_mfma_f32_16x16x32_bf16 v[26:29], v[138:141], v[214:217], v[26:29]
	v_mfma_f32_16x16x32_bf16 v[42:45], v[138:141], v[184:187], v[42:45]
	v_mfma_f32_16x16x32_bf16 v[42:45], v[142:145], v[210:213], v[42:45]
	v_mfma_f32_16x16x32_bf16 v[58:61], v[142:145], v[180:183], v[58:61]
	v_mfma_f32_16x16x32_bf16 v[58:61], v[138:141], v[176:179], v[58:61]
	v_mfma_f32_16x16x32_bf16 v[46:49], v[168:171], v[176:179], v[46:49]
	v_mfma_f32_16x16x32_bf16 v[46:49], v[172:175], v[180:183], v[46:49]
	v_mfma_f32_16x16x32_bf16 v[30:33], v[172:175], v[210:213], v[30:33]
	v_mfma_f32_16x16x32_bf16 v[30:33], v[168:171], v[184:187], v[30:33]
	v_mfma_f32_16x16x32_bf16 v[14:17], v[168:171], v[214:217], v[14:17]
	v_mfma_f32_16x16x32_bf16 v[14:17], v[172:175], v[218:221], v[14:17]
	v_mfma_f32_16x16x32_bf16 v[2:5], v[172:175], v[226:229], v[2:5]
	v_mfma_f32_16x16x32_bf16 v[2:5], v[168:171], v[222:225], v[2:5]
	v_mfma_f32_16x16x32_bf16 v[6:9], v[156:159], v[222:225], v[6:9]
	v_mfma_f32_16x16x32_bf16 v[6:9], v[164:167], v[226:229], v[6:9]
	v_mfma_f32_16x16x32_bf16 v[22:25], v[164:167], v[218:221], v[22:25]
	v_mfma_f32_16x16x32_bf16 v[22:25], v[156:159], v[214:217], v[22:25]
	v_mfma_f32_16x16x32_bf16 v[38:41], v[156:159], v[184:187], v[38:41]
	v_mfma_f32_16x16x32_bf16 v[38:41], v[164:167], v[210:213], v[38:41]
	v_mfma_f32_16x16x32_bf16 v[54:57], v[164:167], v[180:183], v[54:57]
	v_mfma_f32_16x16x32_bf16 v[54:57], v[156:159], v[176:179], v[54:57]
	s_setprio 0
	s_barrier
	s_add_i32 s56, 0, 0x18000
	s_add_i32 s75, 0, 0x1c000
	s_add_u32 s12, s62, 0x40000
	s_addc_u32 s13, s63, 0
	s_mov_b32 m0, s64
	s_nop 0
	global_load_lds_dwordx4 v146, s[12:13]
	s_mov_b32 m0, s65
	s_nop 0
	global_load_lds_dwordx4 v148, s[12:13]
	v_add_u32_e32 v142, s56, v160
	v_add_u32_e32 v163, s75, v160
	ds_read_b128 v[130:133], v142
	ds_read_b128 v[134:137], v142 offset:1024
	ds_read_b128 v[138:141], v142 offset:2048
	ds_read_b128 v[142:145], v142 offset:3072
	ds_read_b128 v[156:159], v163
	ds_read_b128 v[164:167], v163 offset:1024
	ds_read_b128 v[168:171], v163 offset:2048
	ds_read_b128 v[172:175], v163 offset:3072
	ds_read_b128 v[176:179], v162 offset:32768
	ds_read_b128 v[180:183], v162 offset:33792
	ds_read_b128 v[184:187], v162 offset:34816
	ds_read_b128 v[210:213], v162 offset:35840
	ds_read_b128 v[214:217], v162 offset:36864
	ds_read_b128 v[218:221], v162 offset:37888
	ds_read_b128 v[222:225], v162 offset:38912
	ds_read_b128 v[226:229], v162 offset:39936
	s_waitcnt vmcnt(8)
	s_waitcnt lgkmcnt(0)
	s_barrier
	s_setprio 1
	s_waitcnt lgkmcnt(0)
	v_mfma_f32_16x16x32_bf16 v[126:129], v[130:133], v[176:179], v[126:129]
	v_mfma_f32_16x16x32_bf16 v[126:129], v[134:137], v[180:183], v[126:129]
	v_mfma_f32_16x16x32_bf16 v[114:117], v[134:137], v[210:213], v[114:117]
	v_mfma_f32_16x16x32_bf16 v[114:117], v[130:133], v[184:187], v[114:117]
	v_mfma_f32_16x16x32_bf16 v[98:101], v[130:133], v[214:217], v[98:101]
	v_mfma_f32_16x16x32_bf16 v[98:101], v[134:137], v[218:221], v[98:101]
	v_mfma_f32_16x16x32_bf16 v[82:85], v[134:137], v[226:229], v[82:85]
	v_mfma_f32_16x16x32_bf16 v[82:85], v[130:133], v[222:225], v[82:85]
	v_mfma_f32_16x16x32_bf16 v[74:77], v[138:141], v[222:225], v[74:77]
	v_mfma_f32_16x16x32_bf16 v[74:77], v[142:145], v[226:229], v[74:77]
	v_mfma_f32_16x16x32_bf16 v[90:93], v[142:145], v[218:221], v[90:93]
	v_mfma_f32_16x16x32_bf16 v[90:93], v[138:141], v[214:217], v[90:93]
	v_mfma_f32_16x16x32_bf16 v[106:109], v[138:141], v[184:187], v[106:109]
	v_mfma_f32_16x16x32_bf16 v[106:109], v[142:145], v[210:213], v[106:109]
	v_mfma_f32_16x16x32_bf16 v[122:125], v[142:145], v[180:183], v[122:125]
	v_mfma_f32_16x16x32_bf16 v[122:125], v[138:141], v[176:179], v[122:125]
	v_mfma_f32_16x16x32_bf16 v[110:113], v[168:171], v[176:179], v[110:113]
	v_mfma_f32_16x16x32_bf16 v[110:113], v[172:175], v[180:183], v[110:113]
	v_mfma_f32_16x16x32_bf16 v[94:97], v[172:175], v[210:213], v[94:97]
	v_mfma_f32_16x16x32_bf16 v[94:97], v[168:171], v[184:187], v[94:97]
	v_mfma_f32_16x16x32_bf16 v[78:81], v[168:171], v[214:217], v[78:81]
	v_mfma_f32_16x16x32_bf16 v[78:81], v[172:175], v[218:221], v[78:81]
	v_mfma_f32_16x16x32_bf16 v[66:69], v[172:175], v[226:229], v[66:69]
	v_mfma_f32_16x16x32_bf16 v[66:69], v[168:171], v[222:225], v[66:69]
	v_mfma_f32_16x16x32_bf16 v[70:73], v[156:159], v[222:225], v[70:73]
	v_mfma_f32_16x16x32_bf16 v[70:73], v[164:167], v[226:229], v[70:73]
	v_mfma_f32_16x16x32_bf16 v[86:89], v[164:167], v[218:221], v[86:89]
	v_mfma_f32_16x16x32_bf16 v[86:89], v[156:159], v[214:217], v[86:89]
	v_mfma_f32_16x16x32_bf16 v[102:105], v[156:159], v[184:187], v[102:105]
	v_mfma_f32_16x16x32_bf16 v[102:105], v[164:167], v[210:213], v[102:105]
	v_mfma_f32_16x16x32_bf16 v[118:121], v[164:167], v[180:183], v[118:121]
	v_mfma_f32_16x16x32_bf16 v[118:121], v[156:159], v[176:179], v[118:121]
	s_setprio 0
	s_barrier
	s_add_i32 s12, s56, s59
	s_mov_b32 m0, s12
	s_nop 0
	global_load_lds_dwordx4 v231, s[54:55]
	s_add_i32 m0, s12, 0x2000
	s_add_u32 s12, s54, 0x40080
	s_addc_u32 s13, s55, 0
	global_load_lds_dwordx4 v230, s[54:55]
	s_add_i32 s54, s75, s59
	s_mov_b32 m0, s54
	s_nop 0
	global_load_lds_dwordx4 v190, s[12:13]
	s_add_i32 m0, s54, 0x2000
	s_nop 0
	global_load_lds_dwordx4 v150, s[12:13]
	s_mov_b32 m0, s66
	s_nop 0
	global_load_lds_dwordx4 v188, s[62:63]
	s_mov_b32 m0, s68
	s_nop 0
	global_load_lds_dwordx4 v189, s[62:63]
	ds_read_b128 v[176:179], v162 offset:49152
	ds_read_b128 v[180:183], v162 offset:50176
	ds_read_b128 v[184:187], v162 offset:51200
	ds_read_b128 v[210:213], v162 offset:52224
	ds_read_b128 v[214:217], v162 offset:53248
	ds_read_b128 v[218:221], v162 offset:54272
	ds_read_b128 v[222:225], v162 offset:55296
	ds_read_b128 v[226:229], v162 offset:56320
	s_waitcnt vmcnt(8)
	s_waitcnt lgkmcnt(0)
	s_barrier
	s_setprio 1
	s_waitcnt lgkmcnt(0)
	v_mfma_f32_16x16x32_bf16 v[62:65], v[130:133], v[176:179], v[62:65]
	v_mfma_f32_16x16x32_bf16 v[62:65], v[134:137], v[180:183], v[62:65]
	v_mfma_f32_16x16x32_bf16 v[50:53], v[134:137], v[210:213], v[50:53]
	v_mfma_f32_16x16x32_bf16 v[50:53], v[130:133], v[184:187], v[50:53]
	v_mfma_f32_16x16x32_bf16 v[34:37], v[130:133], v[214:217], v[34:37]
	v_mfma_f32_16x16x32_bf16 v[34:37], v[134:137], v[218:221], v[34:37]
	v_mfma_f32_16x16x32_bf16 v[18:21], v[134:137], v[226:229], v[18:21]
	v_mfma_f32_16x16x32_bf16 v[18:21], v[130:133], v[222:225], v[18:21]
	v_mfma_f32_16x16x32_bf16 v[10:13], v[138:141], v[222:225], v[10:13]
	v_mfma_f32_16x16x32_bf16 v[10:13], v[142:145], v[226:229], v[10:13]
	v_mfma_f32_16x16x32_bf16 v[26:29], v[142:145], v[218:221], v[26:29]
	v_mfma_f32_16x16x32_bf16 v[26:29], v[138:141], v[214:217], v[26:29]
	v_mfma_f32_16x16x32_bf16 v[42:45], v[138:141], v[184:187], v[42:45]
	v_mfma_f32_16x16x32_bf16 v[42:45], v[142:145], v[210:213], v[42:45]
	v_mfma_f32_16x16x32_bf16 v[58:61], v[142:145], v[180:183], v[58:61]
	v_mfma_f32_16x16x32_bf16 v[58:61], v[138:141], v[176:179], v[58:61]
	v_mfma_f32_16x16x32_bf16 v[46:49], v[168:171], v[176:179], v[46:49]
	v_mfma_f32_16x16x32_bf16 v[46:49], v[172:175], v[180:183], v[46:49]
	v_mfma_f32_16x16x32_bf16 v[30:33], v[172:175], v[210:213], v[30:33]
	v_mfma_f32_16x16x32_bf16 v[30:33], v[168:171], v[184:187], v[30:33]
	v_mfma_f32_16x16x32_bf16 v[14:17], v[168:171], v[214:217], v[14:17]
	v_mfma_f32_16x16x32_bf16 v[14:17], v[172:175], v[218:221], v[14:17]
	v_mfma_f32_16x16x32_bf16 v[2:5], v[172:175], v[226:229], v[2:5]
	v_mfma_f32_16x16x32_bf16 v[2:5], v[168:171], v[222:225], v[2:5]
	v_mfma_f32_16x16x32_bf16 v[6:9], v[156:159], v[222:225], v[6:9]
	v_mfma_f32_16x16x32_bf16 v[6:9], v[164:167], v[226:229], v[6:9]
	v_mfma_f32_16x16x32_bf16 v[22:25], v[164:167], v[218:221], v[22:25]
	v_mfma_f32_16x16x32_bf16 v[22:25], v[156:159], v[214:217], v[22:25]
	v_mfma_f32_16x16x32_bf16 v[38:41], v[156:159], v[184:187], v[38:41]
	v_mfma_f32_16x16x32_bf16 v[38:41], v[164:167], v[210:213], v[38:41]
	v_mfma_f32_16x16x32_bf16 v[54:57], v[164:167], v[180:183], v[54:57]
	v_mfma_f32_16x16x32_bf16 v[54:57], v[156:159], v[176:179], v[54:57]
	s_setprio 0
	s_barrier
	s_add_i32 s74, s74, 2
	s_add_u32 s40, s40, 0x100
	s_addc_u32 s41, s41, 0
	s_add_u32 s73, s73, 0x100
	s_addc_u32 s61, s61, 0
	s_cmp_gt_u32 s74, 13
	s_cbranch_scc0 .LBB0_692
	s_and_b64 vcc, exec, s[30:31]
	s_cbranch_vccz .LBB0_695
	s_barrier

.LBB0_776:
	s_ashr_i32 s43, s42, 31
	s_lshl_b64 s[12:13], s[42:43], 21
	s_add_u32 s44, s57, s12
	s_addc_u32 s45, s58, s13
	s_and_b64 s[12:13], s[38:39], exec
	s_cselect_b32 s43, s45, s51
	s_cselect_b32 s49, s44, s50
	s_ashr_i32 s41, s40, 31
	s_lshl_b64 s[12:13], s[40:41], 21
	s_add_u32 s46, s59, s12
	s_addc_u32 s47, s60, s13
	s_and_b64 s[12:13], s[38:39], exec
	s_cselect_b32 s41, s47, s53
	s_cselect_b32 s70, s46, s52
	s_add_u32 s50, s50, 0x100080
	s_addc_u32 s51, s51, 0
	s_add_u32 s71, s52, 0x100
	v_mov_b32_e32 v2, 0
	s_addc_u32 s61, s53, 0
	s_mov_b32 s72, -2
	v_mov_b32_e32 v3, v2
	v_mov_b32_e32 v4, v2
	v_mov_b32_e32 v5, v2
	v_mov_b32_e32 v6, v2
	v_mov_b32_e32 v7, v2
	v_mov_b32_e32 v8, v2
	v_mov_b32_e32 v9, v2
	v_mov_b32_e32 v14, v2
	v_mov_b32_e32 v15, v2
	v_mov_b32_e32 v16, v2
	v_mov_b32_e32 v17, v2
	v_mov_b32_e32 v22, v2
	v_mov_b32_e32 v23, v2
	v_mov_b32_e32 v24, v2
	v_mov_b32_e32 v25, v2
	v_mov_b32_e32 v30, v2
	v_mov_b32_e32 v31, v2
	v_mov_b32_e32 v32, v2
	v_mov_b32_e32 v33, v2
	v_mov_b32_e32 v38, v2
	v_mov_b32_e32 v39, v2
	v_mov_b32_e32 v40, v2
	v_mov_b32_e32 v41, v2
	v_mov_b32_e32 v46, v2
	v_mov_b32_e32 v47, v2
	v_mov_b32_e32 v48, v2
	v_mov_b32_e32 v49, v2
	v_mov_b32_e32 v54, v2
	v_mov_b32_e32 v55, v2
	v_mov_b32_e32 v56, v2
	v_mov_b32_e32 v57, v2
	v_mov_b32_e32 v10, v2
	v_mov_b32_e32 v11, v2
	v_mov_b32_e32 v12, v2
	v_mov_b32_e32 v13, v2
	v_mov_b32_e32 v18, v2
	v_mov_b32_e32 v19, v2
	v_mov_b32_e32 v20, v2
	v_mov_b32_e32 v21, v2
	v_mov_b32_e32 v26, v2
	v_mov_b32_e32 v27, v2
	v_mov_b32_e32 v28, v2
	v_mov_b32_e32 v29, v2
	v_mov_b32_e32 v34, v2
	v_mov_b32_e32 v35, v2
	v_mov_b32_e32 v36, v2
	v_mov_b32_e32 v37, v2
	v_mov_b32_e32 v42, v2
	v_mov_b32_e32 v43, v2
	v_mov_b32_e32 v44, v2
	v_mov_b32_e32 v45, v2
	v_mov_b32_e32 v50, v2
	v_mov_b32_e32 v51, v2
	v_mov_b32_e32 v52, v2
	v_mov_b32_e32 v53, v2
	v_mov_b32_e32 v58, v2
	v_mov_b32_e32 v59, v2
	v_mov_b32_e32 v60, v2
	v_mov_b32_e32 v61, v2
	v_mov_b32_e32 v62, v2
	v_mov_b32_e32 v63, v2
	v_mov_b32_e32 v64, v2
	v_mov_b32_e32 v65, v2
	v_mov_b32_e32 v66, v2
	v_mov_b32_e32 v67, v2
	v_mov_b32_e32 v68, v2
	v_mov_b32_e32 v69, v2
	v_mov_b32_e32 v70, v2
	v_mov_b32_e32 v71, v2
	v_mov_b32_e32 v72, v2
	v_mov_b32_e32 v73, v2
	v_mov_b32_e32 v78, v2
	v_mov_b32_e32 v79, v2
	v_mov_b32_e32 v80, v2
	v_mov_b32_e32 v81, v2
	v_mov_b32_e32 v86, v2
	v_mov_b32_e32 v87, v2
	v_mov_b32_e32 v88, v2
	v_mov_b32_e32 v89, v2
	v_mov_b32_e32 v94, v2
	v_mov_b32_e32 v95, v2
	v_mov_b32_e32 v96, v2
	v_mov_b32_e32 v97, v2
	v_mov_b32_e32 v102, v2
	v_mov_b32_e32 v103, v2
	v_mov_b32_e32 v104, v2
	v_mov_b32_e32 v105, v2
	v_mov_b32_e32 v114, v2
	v_mov_b32_e32 v115, v2
	v_mov_b32_e32 v116, v2
	v_mov_b32_e32 v117, v2
	v_mov_b32_e32 v118, v2
	v_mov_b32_e32 v119, v2
	v_mov_b32_e32 v120, v2
	v_mov_b32_e32 v121, v2
	v_mov_b32_e32 v74, v2
	v_mov_b32_e32 v75, v2
	v_mov_b32_e32 v76, v2
	v_mov_b32_e32 v77, v2
	v_mov_b32_e32 v82, v2
	v_mov_b32_e32 v83, v2
	v_mov_b32_e32 v84, v2
	v_mov_b32_e32 v85, v2
	v_mov_b32_e32 v90, v2
	v_mov_b32_e32 v91, v2
	v_mov_b32_e32 v92, v2
	v_mov_b32_e32 v93, v2
	v_mov_b32_e32 v98, v2
	v_mov_b32_e32 v99, v2
	v_mov_b32_e32 v100, v2
	v_mov_b32_e32 v101, v2
	v_mov_b32_e32 v106, v2
	v_mov_b32_e32 v107, v2
	v_mov_b32_e32 v108, v2
	v_mov_b32_e32 v109, v2
	v_mov_b32_e32 v110, v2
	v_mov_b32_e32 v111, v2
	v_mov_b32_e32 v112, v2
	v_mov_b32_e32 v113, v2
	v_mov_b32_e32 v122, v2
	v_mov_b32_e32 v123, v2
	v_mov_b32_e32 v124, v2
	v_mov_b32_e32 v125, v2
	v_mov_b32_e32 v126, v2
	v_mov_b32_e32 v127, v2
	v_mov_b32_e32 v128, v2
	v_mov_b32_e32 v129, v2
	v_add_u32_e32 v224, 0x80, v190
	v_add_u32_e32 v225, 0x80, v210
	v_add_u32_e32 v226, 0x80, v212
	v_add_u32_e32 v227, 0x80, v214
.LBB0_777:
	s_add_u32 s12, s50, 0xfff00080
	s_addc_u32 s13, s51, -1
	s_add_i32 s56, 0, 0x10000
	s_cmp_eq_u32 s72, 60
	s_cselect_b32 s55, s43, s13
	s_cselect_b32 s54, s49, s12
	s_cselect_b32 s53, s41, s61
	s_cselect_b32 s52, s70, s71
	s_add_i32 s73, 0, 0x14000
	s_add_i32 m0, s33, 0xc000
	s_nop 0
	global_load_lds_dwordx4 v216, s[50:51]
	s_add_i32 m0, s33, 0xe000
	s_nop 0
	global_load_lds_dwordx4 v218, s[50:51]
	v_add_u32_e32 v142, s56, v193
	v_add_u32_e32 v158, s73, v193
	ds_read_b128 v[130:133], v142
	ds_read_b128 v[134:137], v142 offset:1024
	ds_read_b128 v[138:141], v142 offset:2048
	ds_read_b128 v[142:145], v142 offset:3072
	ds_read_b128 v[146:149], v158
	ds_read_b128 v[150:153], v158 offset:1024
	ds_read_b128 v[154:157], v158 offset:2048
	ds_read_b128 v[158:161], v158 offset:3072
	ds_read_b128 v[162:165], v197
	ds_read_b128 v[166:169], v197 offset:1024
	ds_read_b128 v[170:173], v197 offset:2048
	ds_read_b128 v[174:177], v197 offset:3072
	ds_read_b128 v[178:181], v197 offset:4096
	ds_read_b128 v[182:185], v197 offset:5120
	ds_read_b128 v[186:189], v197 offset:6144
	ds_read_b128 v[220:223], v197 offset:7168
	s_waitcnt vmcnt(8)
	s_waitcnt lgkmcnt(0)
	s_barrier
	s_setprio 1
	s_waitcnt lgkmcnt(0)
	v_mfma_f32_16x16x32_bf16 v[126:129], v[130:133], v[162:165], v[126:129]
	v_mfma_f32_16x16x32_bf16 v[126:129], v[134:137], v[166:169], v[126:129]
	v_mfma_f32_16x16x32_bf16 v[110:113], v[134:137], v[174:177], v[110:113]
	v_mfma_f32_16x16x32_bf16 v[110:113], v[130:133], v[170:173], v[110:113]
	v_mfma_f32_16x16x32_bf16 v[98:101], v[130:133], v[178:181], v[98:101]
	v_mfma_f32_16x16x32_bf16 v[98:101], v[134:137], v[182:185], v[98:101]
	v_mfma_f32_16x16x32_bf16 v[82:85], v[134:137], v[220:223], v[82:85]
	v_mfma_f32_16x16x32_bf16 v[82:85], v[130:133], v[186:189], v[82:85]
	v_mfma_f32_16x16x32_bf16 v[74:77], v[138:141], v[186:189], v[74:77]
	v_mfma_f32_16x16x32_bf16 v[74:77], v[142:145], v[220:223], v[74:77]
	v_mfma_f32_16x16x32_bf16 v[90:93], v[142:145], v[182:185], v[90:93]
	v_mfma_f32_16x16x32_bf16 v[90:93], v[138:141], v[178:181], v[90:93]
	v_mfma_f32_16x16x32_bf16 v[106:109], v[138:141], v[170:173], v[106:109]
	v_mfma_f32_16x16x32_bf16 v[106:109], v[142:145], v[174:177], v[106:109]
	v_mfma_f32_16x16x32_bf16 v[122:125], v[142:145], v[166:169], v[122:125]
	v_mfma_f32_16x16x32_bf16 v[122:125], v[138:141], v[162:165], v[122:125]
	v_mfma_f32_16x16x32_bf16 v[114:117], v[154:157], v[162:165], v[114:117]
	v_mfma_f32_16x16x32_bf16 v[114:117], v[158:161], v[166:169], v[114:117]
	v_mfma_f32_16x16x32_bf16 v[94:97], v[158:161], v[174:177], v[94:97]
	v_mfma_f32_16x16x32_bf16 v[94:97], v[154:157], v[170:173], v[94:97]
	v_mfma_f32_16x16x32_bf16 v[78:81], v[154:157], v[178:181], v[78:81]
	v_mfma_f32_16x16x32_bf16 v[78:81], v[158:161], v[182:185], v[78:81]
	v_mfma_f32_16x16x32_bf16 v[66:69], v[158:161], v[220:223], v[66:69]
	v_mfma_f32_16x16x32_bf16 v[66:69], v[154:157], v[186:189], v[66:69]
	v_mfma_f32_16x16x32_bf16 v[70:73], v[146:149], v[186:189], v[70:73]
	v_mfma_f32_16x16x32_bf16 v[70:73], v[150:153], v[220:223], v[70:73]
	v_mfma_f32_16x16x32_bf16 v[86:89], v[150:153], v[182:185], v[86:89]
	v_mfma_f32_16x16x32_bf16 v[86:89], v[146:149], v[178:181], v[86:89]
	v_mfma_f32_16x16x32_bf16 v[102:105], v[146:149], v[170:173], v[102:105]
	v_mfma_f32_16x16x32_bf16 v[102:105], v[150:153], v[174:177], v[102:105]
	v_mfma_f32_16x16x32_bf16 v[118:121], v[150:153], v[166:169], v[118:121]
	v_mfma_f32_16x16x32_bf16 v[118:121], v[146:149], v[162:165], v[118:121]
	s_setprio 0
	s_barrier
	s_add_i32 s12, s56, s29
	s_mov_b32 m0, s12
	s_nop 0
	global_load_lds_dwordx4 v190, s[52:53]
	s_add_i32 m0, s12, 0x2000
	s_add_u32 s12, s52, 0x100000
	s_addc_u32 s13, s53, 0
	s_add_i32 s56, s73, s29
	global_load_lds_dwordx4 v214, s[52:53]
	s_mov_b32 m0, s56
	s_nop 0
	global_load_lds_dwordx4 v190, s[12:13]
	s_add_i32 m0, s56, 0x2000
	s_nop 0
	global_load_lds_dwordx4 v214, s[12:13]
	s_mov_b32 m0, s33
	s_nop 0
	global_load_lds_dwordx4 v210, s[54:55]
	s_mov_b32 m0, s62
	s_nop 0
	global_load_lds_dwordx4 v212, s[54:55]
	ds_read_b128 v[162:165], v197 offset:16384
	ds_read_b128 v[166:169], v197 offset:17408
	ds_read_b128 v[170:173], v197 offset:18432
	ds_read_b128 v[174:177], v197 offset:19456
	ds_read_b128 v[178:181], v197 offset:20480
	ds_read_b128 v[182:185], v197 offset:21504
	ds_read_b128 v[186:189], v197 offset:22528
	ds_read_b128 v[220:223], v197 offset:23552
	s_waitcnt vmcnt(8)
	s_waitcnt lgkmcnt(0)
	s_barrier
	s_setprio 1
	s_waitcnt lgkmcnt(0)
	v_mfma_f32_16x16x32_bf16 v[62:65], v[130:133], v[162:165], v[62:65]
	v_mfma_f32_16x16x32_bf16 v[62:65], v[134:137], v[166:169], v[62:65]
	v_mfma_f32_16x16x32_bf16 v[50:53], v[134:137], v[174:177], v[50:53]
	v_mfma_f32_16x16x32_bf16 v[50:53], v[130:133], v[170:173], v[50:53]
	v_mfma_f32_16x16x32_bf16 v[34:37], v[130:133], v[178:181], v[34:37]
	v_mfma_f32_16x16x32_bf16 v[34:37], v[134:137], v[182:185], v[34:37]
	v_mfma_f32_16x16x32_bf16 v[18:21], v[134:137], v[220:223], v[18:21]
	v_mfma_f32_16x16x32_bf16 v[18:21], v[130:133], v[186:189], v[18:21]
	v_mfma_f32_16x16x32_bf16 v[10:13], v[138:141], v[186:189], v[10:13]
	v_mfma_f32_16x16x32_bf16 v[10:13], v[142:145], v[220:223], v[10:13]
	v_mfma_f32_16x16x32_bf16 v[26:29], v[142:145], v[182:185], v[26:29]
	v_mfma_f32_16x16x32_bf16 v[26:29], v[138:141], v[178:181], v[26:29]
	v_mfma_f32_16x16x32_bf16 v[42:45], v[138:141], v[170:173], v[42:45]
	v_mfma_f32_16x16x32_bf16 v[42:45], v[142:145], v[174:177], v[42:45]
	v_mfma_f32_16x16x32_bf16 v[58:61], v[142:145], v[166:169], v[58:61]
	v_mfma_f32_16x16x32_bf16 v[58:61], v[138:141], v[162:165], v[58:61]
	v_mfma_f32_16x16x32_bf16 v[46:49], v[154:157], v[162:165], v[46:49]
	v_mfma_f32_16x16x32_bf16 v[46:49], v[158:161], v[166:169], v[46:49]
	v_mfma_f32_16x16x32_bf16 v[30:33], v[158:161], v[174:177], v[30:33]
	v_mfma_f32_16x16x32_bf16 v[30:33], v[154:157], v[170:173], v[30:33]
	v_mfma_f32_16x16x32_bf16 v[14:17], v[154:157], v[178:181], v[14:17]
	v_mfma_f32_16x16x32_bf16 v[14:17], v[158:161], v[182:185], v[14:17]
	v_mfma_f32_16x16x32_bf16 v[2:5], v[158:161], v[220:223], v[2:5]
	v_mfma_f32_16x16x32_bf16 v[2:5], v[154:157], v[186:189], v[2:5]
	v_mfma_f32_16x16x32_bf16 v[6:9], v[146:149], v[186:189], v[6:9]
	v_mfma_f32_16x16x32_bf16 v[6:9], v[150:153], v[220:223], v[6:9]
	v_mfma_f32_16x16x32_bf16 v[22:25], v[150:153], v[182:185], v[22:25]
	v_mfma_f32_16x16x32_bf16 v[22:25], v[146:149], v[178:181], v[22:25]
	v_mfma_f32_16x16x32_bf16 v[38:41], v[146:149], v[170:173], v[38:41]
	v_mfma_f32_16x16x32_bf16 v[38:41], v[150:153], v[174:177], v[38:41]
	v_mfma_f32_16x16x32_bf16 v[54:57], v[150:153], v[166:169], v[54:57]
	v_mfma_f32_16x16x32_bf16 v[54:57], v[146:149], v[162:165], v[54:57]
	s_setprio 0
	s_barrier
	s_add_i32 s56, 0, 0x18000
	s_add_i32 s73, 0, 0x1c000
	s_add_u32 s12, s54, 0x100000
	s_addc_u32 s13, s55, 0
	s_mov_b32 m0, s63
	s_nop 0
	global_load_lds_dwordx4 v210, s[12:13]
	s_mov_b32 m0, s64
	s_nop 0
	global_load_lds_dwordx4 v212, s[12:13]
	v_add_u32_e32 v142, s56, v193
	v_add_u32_e32 v158, s73, v193
	ds_read_b128 v[130:133], v142
	ds_read_b128 v[134:137], v142 offset:1024
	ds_read_b128 v[138:141], v142 offset:2048
	ds_read_b128 v[142:145], v142 offset:3072
	ds_read_b128 v[146:149], v158
	ds_read_b128 v[150:153], v158 offset:1024
	ds_read_b128 v[154:157], v158 offset:2048
	ds_read_b128 v[158:161], v158 offset:3072
	ds_read_b128 v[162:165], v197 offset:32768
	ds_read_b128 v[166:169], v197 offset:33792
	ds_read_b128 v[170:173], v197 offset:34816
	ds_read_b128 v[174:177], v197 offset:35840
	ds_read_b128 v[178:181], v197 offset:36864
	ds_read_b128 v[182:185], v197 offset:37888
	ds_read_b128 v[186:189], v197 offset:38912
	ds_read_b128 v[220:223], v197 offset:39936
	s_waitcnt vmcnt(8)
	s_waitcnt lgkmcnt(0)
	s_barrier
	s_setprio 1
	s_waitcnt lgkmcnt(0)
	v_mfma_f32_16x16x32_bf16 v[126:129], v[130:133], v[162:165], v[126:129]
	v_mfma_f32_16x16x32_bf16 v[126:129], v[134:137], v[166:169], v[126:129]
	v_mfma_f32_16x16x32_bf16 v[110:113], v[134:137], v[174:177], v[110:113]
	v_mfma_f32_16x16x32_bf16 v[110:113], v[130:133], v[170:173], v[110:113]
	v_mfma_f32_16x16x32_bf16 v[98:101], v[130:133], v[178:181], v[98:101]
	v_mfma_f32_16x16x32_bf16 v[98:101], v[134:137], v[182:185], v[98:101]
	v_mfma_f32_16x16x32_bf16 v[82:85], v[134:137], v[220:223], v[82:85]
	v_mfma_f32_16x16x32_bf16 v[82:85], v[130:133], v[186:189], v[82:85]
	v_mfma_f32_16x16x32_bf16 v[74:77], v[138:141], v[186:189], v[74:77]
	v_mfma_f32_16x16x32_bf16 v[74:77], v[142:145], v[220:223], v[74:77]
	v_mfma_f32_16x16x32_bf16 v[90:93], v[142:145], v[182:185], v[90:93]
	v_mfma_f32_16x16x32_bf16 v[90:93], v[138:141], v[178:181], v[90:93]
	v_mfma_f32_16x16x32_bf16 v[106:109], v[138:141], v[170:173], v[106:109]
	v_mfma_f32_16x16x32_bf16 v[106:109], v[142:145], v[174:177], v[106:109]
	v_mfma_f32_16x16x32_bf16 v[122:125], v[142:145], v[166:169], v[122:125]
	v_mfma_f32_16x16x32_bf16 v[122:125], v[138:141], v[162:165], v[122:125]
	v_mfma_f32_16x16x32_bf16 v[114:117], v[154:157], v[162:165], v[114:117]
	v_mfma_f32_16x16x32_bf16 v[114:117], v[158:161], v[166:169], v[114:117]
	v_mfma_f32_16x16x32_bf16 v[94:97], v[158:161], v[174:177], v[94:97]
	v_mfma_f32_16x16x32_bf16 v[94:97], v[154:157], v[170:173], v[94:97]
	v_mfma_f32_16x16x32_bf16 v[78:81], v[154:157], v[178:181], v[78:81]
	v_mfma_f32_16x16x32_bf16 v[78:81], v[158:161], v[182:185], v[78:81]
	v_mfma_f32_16x16x32_bf16 v[66:69], v[158:161], v[220:223], v[66:69]
	v_mfma_f32_16x16x32_bf16 v[66:69], v[154:157], v[186:189], v[66:69]
	v_mfma_f32_16x16x32_bf16 v[70:73], v[146:149], v[186:189], v[70:73]
	v_mfma_f32_16x16x32_bf16 v[70:73], v[150:153], v[220:223], v[70:73]
	v_mfma_f32_16x16x32_bf16 v[86:89], v[150:153], v[182:185], v[86:89]
	v_mfma_f32_16x16x32_bf16 v[86:89], v[146:149], v[178:181], v[86:89]
	v_mfma_f32_16x16x32_bf16 v[102:105], v[146:149], v[170:173], v[102:105]
	v_mfma_f32_16x16x32_bf16 v[102:105], v[150:153], v[174:177], v[102:105]
	v_mfma_f32_16x16x32_bf16 v[118:121], v[150:153], v[166:169], v[118:121]
	v_mfma_f32_16x16x32_bf16 v[118:121], v[146:149], v[162:165], v[118:121]
	s_setprio 0
	s_barrier
	s_add_i32 s12, s56, s29
	s_mov_b32 m0, s12
	s_nop 0
	global_load_lds_dwordx4 v224, s[52:53]
	s_add_i32 m0, s12, 0x2000
	s_add_u32 s12, s52, 0x100080
	s_addc_u32 s13, s53, 0
	global_load_lds_dwordx4 v227, s[52:53]
	s_add_i32 s52, s73, s29
	s_mov_b32 m0, s52
	s_nop 0
	global_load_lds_dwordx4 v190, s[12:13]
	s_add_i32 m0, s52, 0x2000
	s_nop 0
	global_load_lds_dwordx4 v214, s[12:13]
	s_mov_b32 m0, s65
	s_nop 0
	global_load_lds_dwordx4 v225, s[54:55]
	s_mov_b32 m0, s66
	s_nop 0
	global_load_lds_dwordx4 v226, s[54:55]
	ds_read_b128 v[162:165], v197 offset:49152
	ds_read_b128 v[166:169], v197 offset:50176
	ds_read_b128 v[170:173], v197 offset:51200
	ds_read_b128 v[174:177], v197 offset:52224
	ds_read_b128 v[178:181], v197 offset:53248
	ds_read_b128 v[182:185], v197 offset:54272
	ds_read_b128 v[186:189], v197 offset:55296
	ds_read_b128 v[220:223], v197 offset:56320
	s_waitcnt vmcnt(8)
	s_waitcnt lgkmcnt(0)
	s_barrier
	s_setprio 1
	s_waitcnt lgkmcnt(0)
	v_mfma_f32_16x16x32_bf16 v[62:65], v[130:133], v[162:165], v[62:65]
	v_mfma_f32_16x16x32_bf16 v[62:65], v[134:137], v[166:169], v[62:65]
	v_mfma_f32_16x16x32_bf16 v[50:53], v[134:137], v[174:177], v[50:53]
	v_mfma_f32_16x16x32_bf16 v[50:53], v[130:133], v[170:173], v[50:53]
	v_mfma_f32_16x16x32_bf16 v[34:37], v[130:133], v[178:181], v[34:37]
	v_mfma_f32_16x16x32_bf16 v[34:37], v[134:137], v[182:185], v[34:37]
	v_mfma_f32_16x16x32_bf16 v[18:21], v[134:137], v[220:223], v[18:21]
	v_mfma_f32_16x16x32_bf16 v[18:21], v[130:133], v[186:189], v[18:21]
	v_mfma_f32_16x16x32_bf16 v[10:13], v[138:141], v[186:189], v[10:13]
	v_mfma_f32_16x16x32_bf16 v[10:13], v[142:145], v[220:223], v[10:13]
	v_mfma_f32_16x16x32_bf16 v[26:29], v[142:145], v[182:185], v[26:29]
	v_mfma_f32_16x16x32_bf16 v[26:29], v[138:141], v[178:181], v[26:29]
	v_mfma_f32_16x16x32_bf16 v[42:45], v[138:141], v[170:173], v[42:45]
	v_mfma_f32_16x16x32_bf16 v[42:45], v[142:145], v[174:177], v[42:45]
	v_mfma_f32_16x16x32_bf16 v[58:61], v[142:145], v[166:169], v[58:61]
	v_mfma_f32_16x16x32_bf16 v[58:61], v[138:141], v[162:165], v[58:61]
	v_mfma_f32_16x16x32_bf16 v[46:49], v[154:157], v[162:165], v[46:49]
	v_mfma_f32_16x16x32_bf16 v[46:49], v[158:161], v[166:169], v[46:49]
	v_mfma_f32_16x16x32_bf16 v[30:33], v[158:161], v[174:177], v[30:33]
	v_mfma_f32_16x16x32_bf16 v[30:33], v[154:157], v[170:173], v[30:33]
	v_mfma_f32_16x16x32_bf16 v[14:17], v[154:157], v[178:181], v[14:17]
	v_mfma_f32_16x16x32_bf16 v[14:17], v[158:161], v[182:185], v[14:17]
	v_mfma_f32_16x16x32_bf16 v[2:5], v[158:161], v[220:223], v[2:5]
	v_mfma_f32_16x16x32_bf16 v[2:5], v[154:157], v[186:189], v[2:5]
	v_mfma_f32_16x16x32_bf16 v[6:9], v[146:149], v[186:189], v[6:9]
	v_mfma_f32_16x16x32_bf16 v[6:9], v[150:153], v[220:223], v[6:9]
	v_mfma_f32_16x16x32_bf16 v[22:25], v[150:153], v[182:185], v[22:25]
	v_mfma_f32_16x16x32_bf16 v[22:25], v[146:149], v[178:181], v[22:25]
	v_mfma_f32_16x16x32_bf16 v[38:41], v[146:149], v[170:173], v[38:41]
	v_mfma_f32_16x16x32_bf16 v[38:41], v[150:153], v[174:177], v[38:41]
	v_mfma_f32_16x16x32_bf16 v[54:57], v[150:153], v[166:169], v[54:57]
	v_mfma_f32_16x16x32_bf16 v[54:57], v[146:149], v[162:165], v[54:57]
	s_setprio 0
	s_barrier
	s_add_i32 s72, s72, 2
	s_add_u32 s50, s50, 0x100
	s_addc_u32 s51, s51, 0
	s_add_u32 s71, s71, 0x100
	s_addc_u32 s61, s61, 0
	s_cmp_gt_u32 s72, 61
	s_cbranch_scc0 .LBB0_777
	s_and_b64 vcc, exec, s[30:31]
	s_cbranch_vccz .LBB0_780
	s_barrier

.LBB0_901:
	s_ashr_i32 s47, s46, 31
	s_lshl_b64 s[12:13], s[46:47], 21
	s_add_u32 s48, s55, s12
	s_addc_u32 s49, s57, s13
	s_and_b64 s[12:13], s[38:39], exec
	s_cselect_b32 s5, s49, s23
	s_cselect_b32 s10, s48, s22
	s_ashr_i32 s45, s44, 31
	s_lshl_b64 s[12:13], s[44:45], 21
	s_add_u32 s50, s58, s12
	s_addc_u32 s51, s59, s13
	s_and_b64 s[12:13], s[38:39], exec
	s_cselect_b32 s25, s51, s31
	s_cselect_b32 s29, s50, s30
	s_add_u32 s22, s22, 0x100080
	s_addc_u32 s23, s23, 0
	s_add_u32 s33, s30, 0x100
	v_mov_b32_e32 v2, 0
	s_addc_u32 s45, s31, 0
	s_mov_b32 s47, -2
	v_mov_b32_e32 v3, v2
	v_mov_b32_e32 v4, v2
	v_mov_b32_e32 v5, v2
	v_mov_b32_e32 v10, v2
	v_mov_b32_e32 v11, v2
	v_mov_b32_e32 v12, v2
	v_mov_b32_e32 v13, v2
	v_mov_b32_e32 v18, v2
	v_mov_b32_e32 v19, v2
	v_mov_b32_e32 v20, v2
	v_mov_b32_e32 v21, v2
	v_mov_b32_e32 v26, v2
	v_mov_b32_e32 v27, v2
	v_mov_b32_e32 v28, v2
	v_mov_b32_e32 v29, v2
	v_mov_b32_e32 v34, v2
	v_mov_b32_e32 v35, v2
	v_mov_b32_e32 v36, v2
	v_mov_b32_e32 v37, v2
	v_mov_b32_e32 v42, v2
	v_mov_b32_e32 v43, v2
	v_mov_b32_e32 v44, v2
	v_mov_b32_e32 v45, v2
	v_mov_b32_e32 v50, v2
	v_mov_b32_e32 v51, v2
	v_mov_b32_e32 v52, v2
	v_mov_b32_e32 v53, v2
	v_mov_b32_e32 v58, v2
	v_mov_b32_e32 v59, v2
	v_mov_b32_e32 v60, v2
	v_mov_b32_e32 v61, v2
	v_mov_b32_e32 v6, v2
	v_mov_b32_e32 v7, v2
	v_mov_b32_e32 v8, v2
	v_mov_b32_e32 v9, v2
	v_mov_b32_e32 v14, v2
	v_mov_b32_e32 v15, v2
	v_mov_b32_e32 v16, v2
	v_mov_b32_e32 v17, v2
	v_mov_b32_e32 v22, v2
	v_mov_b32_e32 v23, v2
	v_mov_b32_e32 v24, v2
	v_mov_b32_e32 v25, v2
	v_mov_b32_e32 v30, v2
	v_mov_b32_e32 v31, v2
	v_mov_b32_e32 v32, v2
	v_mov_b32_e32 v33, v2
	v_mov_b32_e32 v38, v2
	v_mov_b32_e32 v39, v2
	v_mov_b32_e32 v40, v2
	v_mov_b32_e32 v41, v2
	v_mov_b32_e32 v46, v2
	v_mov_b32_e32 v47, v2
	v_mov_b32_e32 v48, v2
	v_mov_b32_e32 v49, v2
	v_mov_b32_e32 v54, v2
	v_mov_b32_e32 v55, v2
	v_mov_b32_e32 v56, v2
	v_mov_b32_e32 v57, v2
	v_mov_b32_e32 v62, v2
	v_mov_b32_e32 v63, v2
	v_mov_b32_e32 v64, v2
	v_mov_b32_e32 v65, v2
	v_mov_b32_e32 v66, v2
	v_mov_b32_e32 v67, v2
	v_mov_b32_e32 v68, v2
	v_mov_b32_e32 v69, v2
	v_mov_b32_e32 v74, v2
	v_mov_b32_e32 v75, v2
	v_mov_b32_e32 v76, v2
	v_mov_b32_e32 v77, v2
	v_mov_b32_e32 v82, v2
	v_mov_b32_e32 v83, v2
	v_mov_b32_e32 v84, v2
	v_mov_b32_e32 v85, v2
	v_mov_b32_e32 v90, v2
	v_mov_b32_e32 v91, v2
	v_mov_b32_e32 v92, v2
	v_mov_b32_e32 v93, v2
	v_mov_b32_e32 v98, v2
	v_mov_b32_e32 v99, v2
	v_mov_b32_e32 v100, v2
	v_mov_b32_e32 v101, v2
	v_mov_b32_e32 v106, v2
	v_mov_b32_e32 v107, v2
	v_mov_b32_e32 v108, v2
	v_mov_b32_e32 v109, v2
	v_mov_b32_e32 v114, v2
	v_mov_b32_e32 v115, v2
	v_mov_b32_e32 v116, v2
	v_mov_b32_e32 v117, v2
	v_mov_b32_e32 v122, v2
	v_mov_b32_e32 v123, v2
	v_mov_b32_e32 v124, v2
	v_mov_b32_e32 v125, v2
	v_mov_b32_e32 v70, v2
	v_mov_b32_e32 v71, v2
	v_mov_b32_e32 v72, v2
	v_mov_b32_e32 v73, v2
	v_mov_b32_e32 v78, v2
	v_mov_b32_e32 v79, v2
	v_mov_b32_e32 v80, v2
	v_mov_b32_e32 v81, v2
	v_mov_b32_e32 v86, v2
	v_mov_b32_e32 v87, v2
	v_mov_b32_e32 v88, v2
	v_mov_b32_e32 v89, v2
	v_mov_b32_e32 v94, v2
	v_mov_b32_e32 v95, v2
	v_mov_b32_e32 v96, v2
	v_mov_b32_e32 v97, v2
	v_mov_b32_e32 v102, v2
	v_mov_b32_e32 v103, v2
	v_mov_b32_e32 v104, v2
	v_mov_b32_e32 v105, v2
	v_mov_b32_e32 v110, v2
	v_mov_b32_e32 v111, v2
	v_mov_b32_e32 v112, v2
	v_mov_b32_e32 v113, v2
	v_mov_b32_e32 v118, v2
	v_mov_b32_e32 v119, v2
	v_mov_b32_e32 v120, v2
	v_mov_b32_e32 v121, v2
	v_mov_b32_e32 v126, v2
	v_mov_b32_e32 v127, v2
	v_mov_b32_e32 v128, v2
	v_mov_b32_e32 v129, v2
	v_add_u32_e32 v188, 0x80, v130
	v_add_u32_e32 v189, 0x80, v132
	v_add_u32_e32 v230, 0x80, v134
	v_add_u32_e32 v231, 0x80, v190
.LBB0_902:
	s_add_u32 s12, s22, 0xfff00080
	s_addc_u32 s13, s23, -1
	s_add_i32 s56, 0, 0x10000
	s_cmp_eq_u32 s47, 60
	s_cselect_b32 s53, s5, s13
	s_cselect_b32 s52, s10, s12
	s_cselect_b32 s31, s25, s45
	s_cselect_b32 s30, s29, s33
	s_add_i32 s61, 0, 0x14000
	s_add_i32 m0, s63, 0xc000
	s_nop 0
	global_load_lds_dwordx4 v136, s[22:23]
	s_add_i32 m0, s63, 0xe000
	s_nop 0
	global_load_lds_dwordx4 v138, s[22:23]
	v_add_u32_e32 v147, s56, v144
	ds_read_b128 v[140:143], v147
	ds_read_b128 v[148:151], v147 offset:1024
	ds_read_b128 v[152:155], v147 offset:2048
	ds_read_b128 v[156:159], v147 offset:3072
	v_add_u32_e32 v147, s61, v144
	ds_read_b128 v[160:163], v147
	ds_read_b128 v[164:167], v147 offset:1024
	ds_read_b128 v[168:171], v147 offset:2048
	ds_read_b128 v[172:175], v147 offset:3072
	ds_read_b128 v[176:179], v146
	ds_read_b128 v[180:183], v146 offset:1024
	ds_read_b128 v[184:187], v146 offset:2048
	ds_read_b128 v[210:213], v146 offset:3072
	ds_read_b128 v[214:217], v146 offset:4096
	ds_read_b128 v[218:221], v146 offset:5120
	ds_read_b128 v[222:225], v146 offset:6144
	ds_read_b128 v[226:229], v146 offset:7168
	s_waitcnt vmcnt(8)
	s_waitcnt lgkmcnt(0)
	s_barrier
	s_setprio 1
	s_waitcnt lgkmcnt(0)
	v_mfma_f32_16x16x32_bf16 v[126:129], v[140:143], v[176:179], v[126:129]
	v_mfma_f32_16x16x32_bf16 v[126:129], v[148:151], v[180:183], v[126:129]
	v_mfma_f32_16x16x32_bf16 v[110:113], v[148:151], v[210:213], v[110:113]
	v_mfma_f32_16x16x32_bf16 v[110:113], v[140:143], v[184:187], v[110:113]
	v_mfma_f32_16x16x32_bf16 v[94:97], v[140:143], v[214:217], v[94:97]
	v_mfma_f32_16x16x32_bf16 v[94:97], v[148:151], v[218:221], v[94:97]
	v_mfma_f32_16x16x32_bf16 v[78:81], v[148:151], v[226:229], v[78:81]
	v_mfma_f32_16x16x32_bf16 v[78:81], v[140:143], v[222:225], v[78:81]
	v_mfma_f32_16x16x32_bf16 v[70:73], v[152:155], v[222:225], v[70:73]
	v_mfma_f32_16x16x32_bf16 v[70:73], v[156:159], v[226:229], v[70:73]
	v_mfma_f32_16x16x32_bf16 v[86:89], v[156:159], v[218:221], v[86:89]
	v_mfma_f32_16x16x32_bf16 v[86:89], v[152:155], v[214:217], v[86:89]
	v_mfma_f32_16x16x32_bf16 v[102:105], v[152:155], v[184:187], v[102:105]
	v_mfma_f32_16x16x32_bf16 v[102:105], v[156:159], v[210:213], v[102:105]
	v_mfma_f32_16x16x32_bf16 v[118:121], v[156:159], v[180:183], v[118:121]
	v_mfma_f32_16x16x32_bf16 v[118:121], v[152:155], v[176:179], v[118:121]
	v_mfma_f32_16x16x32_bf16 v[114:117], v[168:171], v[176:179], v[114:117]
	v_mfma_f32_16x16x32_bf16 v[114:117], v[172:175], v[180:183], v[114:117]
	v_mfma_f32_16x16x32_bf16 v[98:101], v[172:175], v[210:213], v[98:101]
	v_mfma_f32_16x16x32_bf16 v[98:101], v[168:171], v[184:187], v[98:101]
	v_mfma_f32_16x16x32_bf16 v[82:85], v[168:171], v[214:217], v[82:85]
	v_mfma_f32_16x16x32_bf16 v[82:85], v[172:175], v[218:221], v[82:85]
	v_mfma_f32_16x16x32_bf16 v[66:69], v[172:175], v[226:229], v[66:69]
	v_mfma_f32_16x16x32_bf16 v[66:69], v[168:171], v[222:225], v[66:69]
	v_mfma_f32_16x16x32_bf16 v[74:77], v[160:163], v[222:225], v[74:77]
	v_mfma_f32_16x16x32_bf16 v[74:77], v[164:167], v[226:229], v[74:77]
	v_mfma_f32_16x16x32_bf16 v[90:93], v[164:167], v[218:221], v[90:93]
	v_mfma_f32_16x16x32_bf16 v[90:93], v[160:163], v[214:217], v[90:93]
	v_mfma_f32_16x16x32_bf16 v[106:109], v[160:163], v[184:187], v[106:109]
	v_mfma_f32_16x16x32_bf16 v[106:109], v[164:167], v[210:213], v[106:109]
	v_mfma_f32_16x16x32_bf16 v[122:125], v[164:167], v[180:183], v[122:125]
	v_mfma_f32_16x16x32_bf16 v[122:125], v[160:163], v[176:179], v[122:125]
	s_setprio 0
	s_barrier
	s_add_i32 s12, s56, s60
	s_mov_b32 m0, s12
	s_nop 0
	global_load_lds_dwordx4 v190, s[30:31]
	s_add_i32 m0, s12, 0x2000
	s_add_u32 s12, s30, 0x100000
	s_addc_u32 s13, s31, 0
	s_add_i32 s56, s61, s60
	global_load_lds_dwordx4 v130, s[30:31]
	s_mov_b32 m0, s56
	s_nop 0
	global_load_lds_dwordx4 v190, s[12:13]
	s_add_i32 m0, s56, 0x2000
	s_nop 0
	global_load_lds_dwordx4 v130, s[12:13]
	s_mov_b32 m0, s63
	s_nop 0
	global_load_lds_dwordx4 v134, s[52:53]
	s_mov_b32 m0, s64
	s_nop 0
	global_load_lds_dwordx4 v132, s[52:53]
	ds_read_b128 v[176:179], v146 offset:16384
	ds_read_b128 v[180:183], v146 offset:17408
	ds_read_b128 v[184:187], v146 offset:18432
	ds_read_b128 v[210:213], v146 offset:19456
	ds_read_b128 v[214:217], v146 offset:20480
	ds_read_b128 v[218:221], v146 offset:21504
	ds_read_b128 v[222:225], v146 offset:22528
	ds_read_b128 v[226:229], v146 offset:23552
	s_waitcnt vmcnt(8)
	s_waitcnt lgkmcnt(0)
	s_barrier
	s_setprio 1
	s_waitcnt lgkmcnt(0)
	v_mfma_f32_16x16x32_bf16 v[62:65], v[140:143], v[176:179], v[62:65]
	v_mfma_f32_16x16x32_bf16 v[62:65], v[148:151], v[180:183], v[62:65]
	v_mfma_f32_16x16x32_bf16 v[46:49], v[148:151], v[210:213], v[46:49]
	v_mfma_f32_16x16x32_bf16 v[46:49], v[140:143], v[184:187], v[46:49]
	v_mfma_f32_16x16x32_bf16 v[30:33], v[140:143], v[214:217], v[30:33]
	v_mfma_f32_16x16x32_bf16 v[30:33], v[148:151], v[218:221], v[30:33]
	v_mfma_f32_16x16x32_bf16 v[14:17], v[148:151], v[226:229], v[14:17]
	v_mfma_f32_16x16x32_bf16 v[14:17], v[140:143], v[222:225], v[14:17]
	v_mfma_f32_16x16x32_bf16 v[6:9], v[152:155], v[222:225], v[6:9]
	v_mfma_f32_16x16x32_bf16 v[6:9], v[156:159], v[226:229], v[6:9]
	v_mfma_f32_16x16x32_bf16 v[22:25], v[156:159], v[218:221], v[22:25]
	v_mfma_f32_16x16x32_bf16 v[22:25], v[152:155], v[214:217], v[22:25]
	v_mfma_f32_16x16x32_bf16 v[38:41], v[152:155], v[184:187], v[38:41]
	v_mfma_f32_16x16x32_bf16 v[38:41], v[156:159], v[210:213], v[38:41]
	v_mfma_f32_16x16x32_bf16 v[54:57], v[156:159], v[180:183], v[54:57]
	v_mfma_f32_16x16x32_bf16 v[54:57], v[152:155], v[176:179], v[54:57]
	v_mfma_f32_16x16x32_bf16 v[50:53], v[168:171], v[176:179], v[50:53]
	v_mfma_f32_16x16x32_bf16 v[50:53], v[172:175], v[180:183], v[50:53]
	v_mfma_f32_16x16x32_bf16 v[34:37], v[172:175], v[210:213], v[34:37]
	v_mfma_f32_16x16x32_bf16 v[34:37], v[168:171], v[184:187], v[34:37]
	v_mfma_f32_16x16x32_bf16 v[18:21], v[168:171], v[214:217], v[18:21]
	v_mfma_f32_16x16x32_bf16 v[18:21], v[172:175], v[218:221], v[18:21]
	v_mfma_f32_16x16x32_bf16 v[2:5], v[172:175], v[226:229], v[2:5]
	v_mfma_f32_16x16x32_bf16 v[2:5], v[168:171], v[222:225], v[2:5]
	v_mfma_f32_16x16x32_bf16 v[10:13], v[160:163], v[222:225], v[10:13]
	v_mfma_f32_16x16x32_bf16 v[10:13], v[164:167], v[226:229], v[10:13]
	v_mfma_f32_16x16x32_bf16 v[26:29], v[164:167], v[218:221], v[26:29]
	v_mfma_f32_16x16x32_bf16 v[26:29], v[160:163], v[214:217], v[26:29]
	v_mfma_f32_16x16x32_bf16 v[42:45], v[160:163], v[184:187], v[42:45]
	v_mfma_f32_16x16x32_bf16 v[42:45], v[164:167], v[210:213], v[42:45]
	v_mfma_f32_16x16x32_bf16 v[58:61], v[164:167], v[180:183], v[58:61]
	v_mfma_f32_16x16x32_bf16 v[58:61], v[160:163], v[176:179], v[58:61]
	s_setprio 0
	s_barrier
	s_add_i32 s56, 0, 0x18000
	s_add_i32 s61, 0, 0x1c000
	s_add_u32 s12, s52, 0x100000
	s_addc_u32 s13, s53, 0
	s_mov_b32 m0, s65
	s_nop 0
	global_load_lds_dwordx4 v134, s[12:13]
	s_mov_b32 m0, s66
	s_nop 0
	global_load_lds_dwordx4 v132, s[12:13]
	v_add_u32_e32 v147, s56, v144
	ds_read_b128 v[140:143], v147
	ds_read_b128 v[148:151], v147 offset:1024
	ds_read_b128 v[152:155], v147 offset:2048
	ds_read_b128 v[156:159], v147 offset:3072
	v_add_u32_e32 v147, s61, v144
	ds_read_b128 v[160:163], v147
	ds_read_b128 v[164:167], v147 offset:1024
	ds_read_b128 v[168:171], v147 offset:2048
	ds_read_b128 v[172:175], v147 offset:3072
	ds_read_b128 v[176:179], v146 offset:32768
	ds_read_b128 v[180:183], v146 offset:33792
	ds_read_b128 v[184:187], v146 offset:34816
	ds_read_b128 v[210:213], v146 offset:35840
	ds_read_b128 v[214:217], v146 offset:36864
	ds_read_b128 v[218:221], v146 offset:37888
	ds_read_b128 v[222:225], v146 offset:38912
	ds_read_b128 v[226:229], v146 offset:39936
	s_waitcnt vmcnt(8)
	s_waitcnt lgkmcnt(0)
	s_barrier
	s_setprio 1
	s_waitcnt lgkmcnt(0)
	v_mfma_f32_16x16x32_bf16 v[126:129], v[140:143], v[176:179], v[126:129]
	v_mfma_f32_16x16x32_bf16 v[126:129], v[148:151], v[180:183], v[126:129]
	v_mfma_f32_16x16x32_bf16 v[110:113], v[148:151], v[210:213], v[110:113]
	v_mfma_f32_16x16x32_bf16 v[110:113], v[140:143], v[184:187], v[110:113]
	v_mfma_f32_16x16x32_bf16 v[94:97], v[140:143], v[214:217], v[94:97]
	v_mfma_f32_16x16x32_bf16 v[94:97], v[148:151], v[218:221], v[94:97]
	v_mfma_f32_16x16x32_bf16 v[78:81], v[148:151], v[226:229], v[78:81]
	v_mfma_f32_16x16x32_bf16 v[78:81], v[140:143], v[222:225], v[78:81]
	v_mfma_f32_16x16x32_bf16 v[70:73], v[152:155], v[222:225], v[70:73]
	v_mfma_f32_16x16x32_bf16 v[70:73], v[156:159], v[226:229], v[70:73]
	v_mfma_f32_16x16x32_bf16 v[86:89], v[156:159], v[218:221], v[86:89]
	v_mfma_f32_16x16x32_bf16 v[86:89], v[152:155], v[214:217], v[86:89]
	v_mfma_f32_16x16x32_bf16 v[102:105], v[152:155], v[184:187], v[102:105]
	v_mfma_f32_16x16x32_bf16 v[102:105], v[156:159], v[210:213], v[102:105]
	v_mfma_f32_16x16x32_bf16 v[118:121], v[156:159], v[180:183], v[118:121]
	v_mfma_f32_16x16x32_bf16 v[118:121], v[152:155], v[176:179], v[118:121]
	v_mfma_f32_16x16x32_bf16 v[114:117], v[168:171], v[176:179], v[114:117]
	v_mfma_f32_16x16x32_bf16 v[114:117], v[172:175], v[180:183], v[114:117]
	v_mfma_f32_16x16x32_bf16 v[98:101], v[172:175], v[210:213], v[98:101]
	v_mfma_f32_16x16x32_bf16 v[98:101], v[168:171], v[184:187], v[98:101]
	v_mfma_f32_16x16x32_bf16 v[82:85], v[168:171], v[214:217], v[82:85]
	v_mfma_f32_16x16x32_bf16 v[82:85], v[172:175], v[218:221], v[82:85]
	v_mfma_f32_16x16x32_bf16 v[66:69], v[172:175], v[226:229], v[66:69]
	v_mfma_f32_16x16x32_bf16 v[66:69], v[168:171], v[222:225], v[66:69]
	v_mfma_f32_16x16x32_bf16 v[74:77], v[160:163], v[222:225], v[74:77]
	v_mfma_f32_16x16x32_bf16 v[74:77], v[164:167], v[226:229], v[74:77]
	v_mfma_f32_16x16x32_bf16 v[90:93], v[164:167], v[218:221], v[90:93]
	v_mfma_f32_16x16x32_bf16 v[90:93], v[160:163], v[214:217], v[90:93]
	v_mfma_f32_16x16x32_bf16 v[106:109], v[160:163], v[184:187], v[106:109]
	v_mfma_f32_16x16x32_bf16 v[106:109], v[164:167], v[210:213], v[106:109]
	v_mfma_f32_16x16x32_bf16 v[122:125], v[164:167], v[180:183], v[122:125]
	v_mfma_f32_16x16x32_bf16 v[122:125], v[160:163], v[176:179], v[122:125]
	s_setprio 0
	s_barrier
	s_add_i32 s12, s56, s60
	s_mov_b32 m0, s12
	s_nop 0
	global_load_lds_dwordx4 v231, s[30:31]
	s_add_i32 m0, s12, 0x2000
	s_add_u32 s12, s30, 0x100080
	s_addc_u32 s13, s31, 0
	global_load_lds_dwordx4 v188, s[30:31]
	s_add_i32 s30, s61, s60
	s_mov_b32 m0, s30
	s_nop 0
	global_load_lds_dwordx4 v190, s[12:13]
	s_add_i32 m0, s30, 0x2000
	s_nop 0
	global_load_lds_dwordx4 v130, s[12:13]
	s_mov_b32 m0, s68
	s_nop 0
	global_load_lds_dwordx4 v230, s[52:53]
	s_mov_b32 m0, s69
	s_nop 0
	global_load_lds_dwordx4 v189, s[52:53]
	ds_read_b128 v[176:179], v146 offset:49152
	ds_read_b128 v[180:183], v146 offset:50176
	ds_read_b128 v[184:187], v146 offset:51200
	ds_read_b128 v[210:213], v146 offset:52224
	ds_read_b128 v[214:217], v146 offset:53248
	ds_read_b128 v[218:221], v146 offset:54272
	ds_read_b128 v[222:225], v146 offset:55296
	ds_read_b128 v[226:229], v146 offset:56320
	s_waitcnt vmcnt(8)
	s_waitcnt lgkmcnt(0)
	s_barrier
	s_setprio 1
	s_waitcnt lgkmcnt(0)
	v_mfma_f32_16x16x32_bf16 v[62:65], v[140:143], v[176:179], v[62:65]
	v_mfma_f32_16x16x32_bf16 v[62:65], v[148:151], v[180:183], v[62:65]
	v_mfma_f32_16x16x32_bf16 v[46:49], v[148:151], v[210:213], v[46:49]
	v_mfma_f32_16x16x32_bf16 v[46:49], v[140:143], v[184:187], v[46:49]
	v_mfma_f32_16x16x32_bf16 v[30:33], v[140:143], v[214:217], v[30:33]
	v_mfma_f32_16x16x32_bf16 v[30:33], v[148:151], v[218:221], v[30:33]
	v_mfma_f32_16x16x32_bf16 v[14:17], v[148:151], v[226:229], v[14:17]
	v_mfma_f32_16x16x32_bf16 v[14:17], v[140:143], v[222:225], v[14:17]
	v_mfma_f32_16x16x32_bf16 v[6:9], v[152:155], v[222:225], v[6:9]
	v_mfma_f32_16x16x32_bf16 v[6:9], v[156:159], v[226:229], v[6:9]
	v_mfma_f32_16x16x32_bf16 v[22:25], v[156:159], v[218:221], v[22:25]
	v_mfma_f32_16x16x32_bf16 v[22:25], v[152:155], v[214:217], v[22:25]
	v_mfma_f32_16x16x32_bf16 v[38:41], v[152:155], v[184:187], v[38:41]
	v_mfma_f32_16x16x32_bf16 v[38:41], v[156:159], v[210:213], v[38:41]
	v_mfma_f32_16x16x32_bf16 v[54:57], v[156:159], v[180:183], v[54:57]
	v_mfma_f32_16x16x32_bf16 v[54:57], v[152:155], v[176:179], v[54:57]
	v_mfma_f32_16x16x32_bf16 v[50:53], v[168:171], v[176:179], v[50:53]
	v_mfma_f32_16x16x32_bf16 v[50:53], v[172:175], v[180:183], v[50:53]
	v_mfma_f32_16x16x32_bf16 v[34:37], v[172:175], v[210:213], v[34:37]
	v_mfma_f32_16x16x32_bf16 v[34:37], v[168:171], v[184:187], v[34:37]
	v_mfma_f32_16x16x32_bf16 v[18:21], v[168:171], v[214:217], v[18:21]
	v_mfma_f32_16x16x32_bf16 v[18:21], v[172:175], v[218:221], v[18:21]
	v_mfma_f32_16x16x32_bf16 v[2:5], v[172:175], v[226:229], v[2:5]
	v_mfma_f32_16x16x32_bf16 v[2:5], v[168:171], v[222:225], v[2:5]
	v_mfma_f32_16x16x32_bf16 v[10:13], v[160:163], v[222:225], v[10:13]
	v_mfma_f32_16x16x32_bf16 v[10:13], v[164:167], v[226:229], v[10:13]
	v_mfma_f32_16x16x32_bf16 v[26:29], v[164:167], v[218:221], v[26:29]
	v_mfma_f32_16x16x32_bf16 v[26:29], v[160:163], v[214:217], v[26:29]
	v_mfma_f32_16x16x32_bf16 v[42:45], v[160:163], v[184:187], v[42:45]
	v_mfma_f32_16x16x32_bf16 v[42:45], v[164:167], v[210:213], v[42:45]
	v_mfma_f32_16x16x32_bf16 v[58:61], v[164:167], v[180:183], v[58:61]
	v_mfma_f32_16x16x32_bf16 v[58:61], v[160:163], v[176:179], v[58:61]
	s_setprio 0
	s_barrier
	s_add_i32 s47, s47, 2
	s_add_u32 s22, s22, 0x100
	s_addc_u32 s23, s23, 0
	s_add_u32 s33, s33, 0x100
	s_addc_u32 s45, s45, 0
	s_cmp_gt_u32 s47, 61
	s_cbranch_scc0 .LBB0_902
	s_and_b64 vcc, exec, s[42:43]
	s_cbranch_vccz .LBB0_905
	s_barrier

.LBB0_982:
	s_add_u32 s61, s46, 0x100
	v_mov_b32_e32 v2, 0
	s_addc_u32 s69, s47, 0
	s_mov_b32 s70, -2
	v_mov_b32_e32 v3, v2
	v_mov_b32_e32 v4, v2
	v_mov_b32_e32 v5, v2
	v_mov_b32_e32 v6, v2
	v_mov_b32_e32 v7, v2
	v_mov_b32_e32 v8, v2
	v_mov_b32_e32 v9, v2
	v_mov_b32_e32 v14, v2
	v_mov_b32_e32 v15, v2
	v_mov_b32_e32 v16, v2
	v_mov_b32_e32 v17, v2
	v_mov_b32_e32 v22, v2
	v_mov_b32_e32 v23, v2
	v_mov_b32_e32 v24, v2
	v_mov_b32_e32 v25, v2
	v_mov_b32_e32 v30, v2
	v_mov_b32_e32 v31, v2
	v_mov_b32_e32 v32, v2
	v_mov_b32_e32 v33, v2
	v_mov_b32_e32 v38, v2
	v_mov_b32_e32 v39, v2
	v_mov_b32_e32 v40, v2
	v_mov_b32_e32 v41, v2
	v_mov_b32_e32 v46, v2
	v_mov_b32_e32 v47, v2
	v_mov_b32_e32 v48, v2
	v_mov_b32_e32 v49, v2
	v_mov_b32_e32 v54, v2
	v_mov_b32_e32 v55, v2
	v_mov_b32_e32 v56, v2
	v_mov_b32_e32 v57, v2
	v_mov_b32_e32 v10, v2
	v_mov_b32_e32 v11, v2
	v_mov_b32_e32 v12, v2
	v_mov_b32_e32 v13, v2
	v_mov_b32_e32 v18, v2
	v_mov_b32_e32 v19, v2
	v_mov_b32_e32 v20, v2
	v_mov_b32_e32 v21, v2
	v_mov_b32_e32 v26, v2
	v_mov_b32_e32 v27, v2
	v_mov_b32_e32 v28, v2
	v_mov_b32_e32 v29, v2
	v_mov_b32_e32 v34, v2
	v_mov_b32_e32 v35, v2
	v_mov_b32_e32 v36, v2
	v_mov_b32_e32 v37, v2
	v_mov_b32_e32 v42, v2
	v_mov_b32_e32 v43, v2
	v_mov_b32_e32 v44, v2
	v_mov_b32_e32 v45, v2
	v_mov_b32_e32 v50, v2
	v_mov_b32_e32 v51, v2
	v_mov_b32_e32 v52, v2
	v_mov_b32_e32 v53, v2
	v_mov_b32_e32 v58, v2
	v_mov_b32_e32 v59, v2
	v_mov_b32_e32 v60, v2
	v_mov_b32_e32 v61, v2
	v_mov_b32_e32 v62, v2
	v_mov_b32_e32 v63, v2
	v_mov_b32_e32 v64, v2
	v_mov_b32_e32 v65, v2
	v_mov_b32_e32 v66, v2
	v_mov_b32_e32 v67, v2
	v_mov_b32_e32 v68, v2
	v_mov_b32_e32 v69, v2
	v_mov_b32_e32 v70, v2
	v_mov_b32_e32 v71, v2
	v_mov_b32_e32 v72, v2
	v_mov_b32_e32 v73, v2
	v_mov_b32_e32 v78, v2
	v_mov_b32_e32 v79, v2
	v_mov_b32_e32 v80, v2
	v_mov_b32_e32 v81, v2
	v_mov_b32_e32 v86, v2
	v_mov_b32_e32 v87, v2
	v_mov_b32_e32 v88, v2
	v_mov_b32_e32 v89, v2
	v_mov_b32_e32 v94, v2
	v_mov_b32_e32 v95, v2
	v_mov_b32_e32 v96, v2
	v_mov_b32_e32 v97, v2
	v_mov_b32_e32 v102, v2
	v_mov_b32_e32 v103, v2
	v_mov_b32_e32 v104, v2
	v_mov_b32_e32 v105, v2
	v_mov_b32_e32 v114, v2
	v_mov_b32_e32 v115, v2
	v_mov_b32_e32 v116, v2
	v_mov_b32_e32 v117, v2
	v_mov_b32_e32 v118, v2
	v_mov_b32_e32 v119, v2
	v_mov_b32_e32 v120, v2
	v_mov_b32_e32 v121, v2
	v_mov_b32_e32 v74, v2
	v_mov_b32_e32 v75, v2
	v_mov_b32_e32 v76, v2
	v_mov_b32_e32 v77, v2
	v_mov_b32_e32 v82, v2
	v_mov_b32_e32 v83, v2
	v_mov_b32_e32 v84, v2
	v_mov_b32_e32 v85, v2
	v_mov_b32_e32 v90, v2
	v_mov_b32_e32 v91, v2
	v_mov_b32_e32 v92, v2
	v_mov_b32_e32 v93, v2
	v_mov_b32_e32 v98, v2
	v_mov_b32_e32 v99, v2
	v_mov_b32_e32 v100, v2
	v_mov_b32_e32 v101, v2
	v_mov_b32_e32 v106, v2
	v_mov_b32_e32 v107, v2
	v_mov_b32_e32 v108, v2
	v_mov_b32_e32 v109, v2
	v_mov_b32_e32 v110, v2
	v_mov_b32_e32 v111, v2
	v_mov_b32_e32 v112, v2
	v_mov_b32_e32 v113, v2
	v_mov_b32_e32 v122, v2
	v_mov_b32_e32 v123, v2
	v_mov_b32_e32 v124, v2
	v_mov_b32_e32 v125, v2
	v_mov_b32_e32 v126, v2
	v_mov_b32_e32 v127, v2
	v_mov_b32_e32 v128, v2
	v_mov_b32_e32 v129, v2
	v_add_u32_e32 v224, 0x80, v190
	v_add_u32_e32 v225, 0x80, v210
	v_add_u32_e32 v226, 0x80, v212
	v_add_u32_e32 v227, 0x80, v214
.LBB0_983:
	s_add_u32 s46, s44, 0x100
	s_addc_u32 s47, s45, 0
	s_add_i32 s12, 0, 0x10000
	s_cmpk_eq_i32 s70, 0xa8
	s_cselect_b32 s51, s41, s47
	s_cselect_b32 s50, s40, s46
	s_cselect_b32 s49, s43, s69
	s_cselect_b32 s48, s42, s61
	s_add_i32 s56, 0, 0x14000
	s_add_i32 m0, s33, 0xc000
	s_nop 0
	global_load_lds_dwordx4 v216, s[44:45]
	s_add_i32 m0, s33, 0xe000
	s_nop 0
	global_load_lds_dwordx4 v218, s[44:45]
	v_add_u32_e32 v142, s12, v193
	v_add_u32_e32 v158, s56, v193
	ds_read_b128 v[130:133], v142
	ds_read_b128 v[134:137], v142 offset:1024
	ds_read_b128 v[138:141], v142 offset:2048
	ds_read_b128 v[142:145], v142 offset:3072
	ds_read_b128 v[146:149], v158
	ds_read_b128 v[150:153], v158 offset:1024
	ds_read_b128 v[154:157], v158 offset:2048
	ds_read_b128 v[158:161], v158 offset:3072
	ds_read_b128 v[162:165], v197
	ds_read_b128 v[166:169], v197 offset:1024
	ds_read_b128 v[170:173], v197 offset:2048
	ds_read_b128 v[174:177], v197 offset:3072
	ds_read_b128 v[178:181], v197 offset:4096
	ds_read_b128 v[182:185], v197 offset:5120
	ds_read_b128 v[186:189], v197 offset:6144
	ds_read_b128 v[220:223], v197 offset:7168
	s_waitcnt vmcnt(8)
	s_waitcnt lgkmcnt(0)
	s_barrier
	s_setprio 1
	s_waitcnt lgkmcnt(0)
	v_mfma_f32_16x16x32_bf16 v[126:129], v[130:133], v[162:165], v[126:129]
	v_mfma_f32_16x16x32_bf16 v[126:129], v[134:137], v[166:169], v[126:129]
	v_mfma_f32_16x16x32_bf16 v[110:113], v[134:137], v[174:177], v[110:113]
	v_mfma_f32_16x16x32_bf16 v[110:113], v[130:133], v[170:173], v[110:113]
	v_mfma_f32_16x16x32_bf16 v[98:101], v[130:133], v[178:181], v[98:101]
	v_mfma_f32_16x16x32_bf16 v[98:101], v[134:137], v[182:185], v[98:101]
	v_mfma_f32_16x16x32_bf16 v[82:85], v[134:137], v[220:223], v[82:85]
	v_mfma_f32_16x16x32_bf16 v[82:85], v[130:133], v[186:189], v[82:85]
	v_mfma_f32_16x16x32_bf16 v[74:77], v[138:141], v[186:189], v[74:77]
	v_mfma_f32_16x16x32_bf16 v[74:77], v[142:145], v[220:223], v[74:77]
	v_mfma_f32_16x16x32_bf16 v[90:93], v[142:145], v[182:185], v[90:93]
	v_mfma_f32_16x16x32_bf16 v[90:93], v[138:141], v[178:181], v[90:93]
	v_mfma_f32_16x16x32_bf16 v[106:109], v[138:141], v[170:173], v[106:109]
	v_mfma_f32_16x16x32_bf16 v[106:109], v[142:145], v[174:177], v[106:109]
	v_mfma_f32_16x16x32_bf16 v[122:125], v[142:145], v[166:169], v[122:125]
	v_mfma_f32_16x16x32_bf16 v[122:125], v[138:141], v[162:165], v[122:125]
	v_mfma_f32_16x16x32_bf16 v[114:117], v[154:157], v[162:165], v[114:117]
	v_mfma_f32_16x16x32_bf16 v[114:117], v[158:161], v[166:169], v[114:117]
	v_mfma_f32_16x16x32_bf16 v[94:97], v[158:161], v[174:177], v[94:97]
	v_mfma_f32_16x16x32_bf16 v[94:97], v[154:157], v[170:173], v[94:97]
	v_mfma_f32_16x16x32_bf16 v[78:81], v[154:157], v[178:181], v[78:81]
	v_mfma_f32_16x16x32_bf16 v[78:81], v[158:161], v[182:185], v[78:81]
	v_mfma_f32_16x16x32_bf16 v[66:69], v[158:161], v[220:223], v[66:69]
	v_mfma_f32_16x16x32_bf16 v[66:69], v[154:157], v[186:189], v[66:69]
	v_mfma_f32_16x16x32_bf16 v[70:73], v[146:149], v[186:189], v[70:73]
	v_mfma_f32_16x16x32_bf16 v[70:73], v[150:153], v[220:223], v[70:73]
	v_mfma_f32_16x16x32_bf16 v[86:89], v[150:153], v[182:185], v[86:89]
	v_mfma_f32_16x16x32_bf16 v[86:89], v[146:149], v[178:181], v[86:89]
	v_mfma_f32_16x16x32_bf16 v[102:105], v[146:149], v[170:173], v[102:105]
	v_mfma_f32_16x16x32_bf16 v[102:105], v[150:153], v[174:177], v[102:105]
	v_mfma_f32_16x16x32_bf16 v[118:121], v[150:153], v[166:169], v[118:121]
	v_mfma_f32_16x16x32_bf16 v[118:121], v[146:149], v[162:165], v[118:121]
	s_setprio 0
	s_barrier
	s_add_i32 s12, s12, s29
	s_mov_b32 m0, s12
	s_nop 0
	global_load_lds_dwordx4 v190, s[48:49]
	s_add_i32 m0, s12, 0x2000
	s_add_u32 s12, s48, 0x2b0000
	s_addc_u32 s13, s49, 0
	s_add_i32 s44, s56, s29
	global_load_lds_dwordx4 v214, s[48:49]
	s_mov_b32 m0, s44
	s_nop 0
	global_load_lds_dwordx4 v190, s[12:13]
	s_add_i32 m0, s44, 0x2000
	s_nop 0
	global_load_lds_dwordx4 v214, s[12:13]
	s_mov_b32 m0, s33
	s_nop 0
	global_load_lds_dwordx4 v210, s[50:51]
	s_mov_b32 m0, s57
	s_nop 0
	global_load_lds_dwordx4 v212, s[50:51]
	ds_read_b128 v[162:165], v197 offset:16384
	ds_read_b128 v[166:169], v197 offset:17408
	ds_read_b128 v[170:173], v197 offset:18432
	ds_read_b128 v[174:177], v197 offset:19456
	ds_read_b128 v[178:181], v197 offset:20480
	ds_read_b128 v[182:185], v197 offset:21504
	ds_read_b128 v[186:189], v197 offset:22528
	ds_read_b128 v[220:223], v197 offset:23552
	s_waitcnt vmcnt(8)
	s_waitcnt lgkmcnt(0)
	s_barrier
	s_setprio 1
	s_waitcnt lgkmcnt(0)
	v_mfma_f32_16x16x32_bf16 v[62:65], v[130:133], v[162:165], v[62:65]
	v_mfma_f32_16x16x32_bf16 v[62:65], v[134:137], v[166:169], v[62:65]
	v_mfma_f32_16x16x32_bf16 v[50:53], v[134:137], v[174:177], v[50:53]
	v_mfma_f32_16x16x32_bf16 v[50:53], v[130:133], v[170:173], v[50:53]
	v_mfma_f32_16x16x32_bf16 v[34:37], v[130:133], v[178:181], v[34:37]
	v_mfma_f32_16x16x32_bf16 v[34:37], v[134:137], v[182:185], v[34:37]
	v_mfma_f32_16x16x32_bf16 v[18:21], v[134:137], v[220:223], v[18:21]
	v_mfma_f32_16x16x32_bf16 v[18:21], v[130:133], v[186:189], v[18:21]
	v_mfma_f32_16x16x32_bf16 v[10:13], v[138:141], v[186:189], v[10:13]
	v_mfma_f32_16x16x32_bf16 v[10:13], v[142:145], v[220:223], v[10:13]
	v_mfma_f32_16x16x32_bf16 v[26:29], v[142:145], v[182:185], v[26:29]
	v_mfma_f32_16x16x32_bf16 v[26:29], v[138:141], v[178:181], v[26:29]
	v_mfma_f32_16x16x32_bf16 v[42:45], v[138:141], v[170:173], v[42:45]
	v_mfma_f32_16x16x32_bf16 v[42:45], v[142:145], v[174:177], v[42:45]
	v_mfma_f32_16x16x32_bf16 v[58:61], v[142:145], v[166:169], v[58:61]
	v_mfma_f32_16x16x32_bf16 v[58:61], v[138:141], v[162:165], v[58:61]
	v_mfma_f32_16x16x32_bf16 v[46:49], v[154:157], v[162:165], v[46:49]
	v_mfma_f32_16x16x32_bf16 v[46:49], v[158:161], v[166:169], v[46:49]
	v_mfma_f32_16x16x32_bf16 v[30:33], v[158:161], v[174:177], v[30:33]
	v_mfma_f32_16x16x32_bf16 v[30:33], v[154:157], v[170:173], v[30:33]
	v_mfma_f32_16x16x32_bf16 v[14:17], v[154:157], v[178:181], v[14:17]
	v_mfma_f32_16x16x32_bf16 v[14:17], v[158:161], v[182:185], v[14:17]
	v_mfma_f32_16x16x32_bf16 v[2:5], v[158:161], v[220:223], v[2:5]
	v_mfma_f32_16x16x32_bf16 v[2:5], v[154:157], v[186:189], v[2:5]
	v_mfma_f32_16x16x32_bf16 v[6:9], v[146:149], v[186:189], v[6:9]
	v_mfma_f32_16x16x32_bf16 v[6:9], v[150:153], v[220:223], v[6:9]
	v_mfma_f32_16x16x32_bf16 v[22:25], v[150:153], v[182:185], v[22:25]
	v_mfma_f32_16x16x32_bf16 v[22:25], v[146:149], v[178:181], v[22:25]
	v_mfma_f32_16x16x32_bf16 v[38:41], v[146:149], v[170:173], v[38:41]
	v_mfma_f32_16x16x32_bf16 v[38:41], v[150:153], v[174:177], v[38:41]
	v_mfma_f32_16x16x32_bf16 v[54:57], v[150:153], v[166:169], v[54:57]
	v_mfma_f32_16x16x32_bf16 v[54:57], v[146:149], v[162:165], v[54:57]
	s_setprio 0
	s_barrier
	s_add_i32 s44, 0, 0x18000
	s_add_i32 s45, 0, 0x1c000
	s_add_u32 s12, s50, 0x2b0000
	s_addc_u32 s13, s51, 0
	s_mov_b32 m0, s58
	s_nop 0
	global_load_lds_dwordx4 v210, s[12:13]
	s_mov_b32 m0, s59
	s_nop 0
	global_load_lds_dwordx4 v212, s[12:13]
	v_add_u32_e32 v142, s44, v193
	v_add_u32_e32 v158, s45, v193
	ds_read_b128 v[130:133], v142
	ds_read_b128 v[134:137], v142 offset:1024
	ds_read_b128 v[138:141], v142 offset:2048
	ds_read_b128 v[142:145], v142 offset:3072
	ds_read_b128 v[146:149], v158
	ds_read_b128 v[150:153], v158 offset:1024
	ds_read_b128 v[154:157], v158 offset:2048
	ds_read_b128 v[158:161], v158 offset:3072
	ds_read_b128 v[162:165], v197 offset:32768
	ds_read_b128 v[166:169], v197 offset:33792
	ds_read_b128 v[170:173], v197 offset:34816
	ds_read_b128 v[174:177], v197 offset:35840
	ds_read_b128 v[178:181], v197 offset:36864
	ds_read_b128 v[182:185], v197 offset:37888
	ds_read_b128 v[186:189], v197 offset:38912
	ds_read_b128 v[220:223], v197 offset:39936
	s_waitcnt vmcnt(8)
	s_waitcnt lgkmcnt(0)
	s_barrier
	s_setprio 1
	s_waitcnt lgkmcnt(0)
	v_mfma_f32_16x16x32_bf16 v[126:129], v[130:133], v[162:165], v[126:129]
	v_mfma_f32_16x16x32_bf16 v[126:129], v[134:137], v[166:169], v[126:129]
	v_mfma_f32_16x16x32_bf16 v[110:113], v[134:137], v[174:177], v[110:113]
	v_mfma_f32_16x16x32_bf16 v[110:113], v[130:133], v[170:173], v[110:113]
	v_mfma_f32_16x16x32_bf16 v[98:101], v[130:133], v[178:181], v[98:101]
	v_mfma_f32_16x16x32_bf16 v[98:101], v[134:137], v[182:185], v[98:101]
	v_mfma_f32_16x16x32_bf16 v[82:85], v[134:137], v[220:223], v[82:85]
	v_mfma_f32_16x16x32_bf16 v[82:85], v[130:133], v[186:189], v[82:85]
	v_mfma_f32_16x16x32_bf16 v[74:77], v[138:141], v[186:189], v[74:77]
	v_mfma_f32_16x16x32_bf16 v[74:77], v[142:145], v[220:223], v[74:77]
	v_mfma_f32_16x16x32_bf16 v[90:93], v[142:145], v[182:185], v[90:93]
	v_mfma_f32_16x16x32_bf16 v[90:93], v[138:141], v[178:181], v[90:93]
	v_mfma_f32_16x16x32_bf16 v[106:109], v[138:141], v[170:173], v[106:109]
	v_mfma_f32_16x16x32_bf16 v[106:109], v[142:145], v[174:177], v[106:109]
	v_mfma_f32_16x16x32_bf16 v[122:125], v[142:145], v[166:169], v[122:125]
	v_mfma_f32_16x16x32_bf16 v[122:125], v[138:141], v[162:165], v[122:125]
	v_mfma_f32_16x16x32_bf16 v[114:117], v[154:157], v[162:165], v[114:117]
	v_mfma_f32_16x16x32_bf16 v[114:117], v[158:161], v[166:169], v[114:117]
	v_mfma_f32_16x16x32_bf16 v[94:97], v[158:161], v[174:177], v[94:97]
	v_mfma_f32_16x16x32_bf16 v[94:97], v[154:157], v[170:173], v[94:97]
	v_mfma_f32_16x16x32_bf16 v[78:81], v[154:157], v[178:181], v[78:81]
	v_mfma_f32_16x16x32_bf16 v[78:81], v[158:161], v[182:185], v[78:81]
	v_mfma_f32_16x16x32_bf16 v[66:69], v[158:161], v[220:223], v[66:69]
	v_mfma_f32_16x16x32_bf16 v[66:69], v[154:157], v[186:189], v[66:69]
	v_mfma_f32_16x16x32_bf16 v[70:73], v[146:149], v[186:189], v[70:73]
	v_mfma_f32_16x16x32_bf16 v[70:73], v[150:153], v[220:223], v[70:73]
	v_mfma_f32_16x16x32_bf16 v[86:89], v[150:153], v[182:185], v[86:89]
	v_mfma_f32_16x16x32_bf16 v[86:89], v[146:149], v[178:181], v[86:89]
	v_mfma_f32_16x16x32_bf16 v[102:105], v[146:149], v[170:173], v[102:105]
	v_mfma_f32_16x16x32_bf16 v[102:105], v[150:153], v[174:177], v[102:105]
	v_mfma_f32_16x16x32_bf16 v[118:121], v[150:153], v[166:169], v[118:121]
	v_mfma_f32_16x16x32_bf16 v[118:121], v[146:149], v[162:165], v[118:121]
	s_setprio 0
	s_barrier
	s_add_i32 s12, s44, s29
	s_mov_b32 m0, s12
	s_nop 0
	global_load_lds_dwordx4 v224, s[48:49]
	s_add_i32 m0, s12, 0x2000
	s_add_u32 s12, s48, 0x2b0080
	s_addc_u32 s13, s49, 0
	s_add_i32 s44, s45, s29
	global_load_lds_dwordx4 v227, s[48:49]
	s_mov_b32 m0, s44
	s_nop 0
	global_load_lds_dwordx4 v190, s[12:13]
	s_add_i32 m0, s44, 0x2000
	s_nop 0
	global_load_lds_dwordx4 v214, s[12:13]
	s_mov_b32 m0, s60
	s_nop 0
	global_load_lds_dwordx4 v225, s[50:51]
	s_mov_b32 m0, s62
	s_nop 0
	global_load_lds_dwordx4 v226, s[50:51]
	ds_read_b128 v[162:165], v197 offset:49152
	ds_read_b128 v[166:169], v197 offset:50176
	ds_read_b128 v[170:173], v197 offset:51200
	ds_read_b128 v[174:177], v197 offset:52224
	ds_read_b128 v[178:181], v197 offset:53248
	ds_read_b128 v[182:185], v197 offset:54272
	ds_read_b128 v[186:189], v197 offset:55296
	ds_read_b128 v[220:223], v197 offset:56320
	s_waitcnt vmcnt(8)
	s_waitcnt lgkmcnt(0)
	s_barrier
	s_setprio 1
	s_waitcnt lgkmcnt(0)
	v_mfma_f32_16x16x32_bf16 v[62:65], v[130:133], v[162:165], v[62:65]
	v_mfma_f32_16x16x32_bf16 v[62:65], v[134:137], v[166:169], v[62:65]
	v_mfma_f32_16x16x32_bf16 v[50:53], v[134:137], v[174:177], v[50:53]
	v_mfma_f32_16x16x32_bf16 v[50:53], v[130:133], v[170:173], v[50:53]
	v_mfma_f32_16x16x32_bf16 v[34:37], v[130:133], v[178:181], v[34:37]
	v_mfma_f32_16x16x32_bf16 v[34:37], v[134:137], v[182:185], v[34:37]
	v_mfma_f32_16x16x32_bf16 v[18:21], v[134:137], v[220:223], v[18:21]
	v_mfma_f32_16x16x32_bf16 v[18:21], v[130:133], v[186:189], v[18:21]
	v_mfma_f32_16x16x32_bf16 v[10:13], v[138:141], v[186:189], v[10:13]
	v_mfma_f32_16x16x32_bf16 v[10:13], v[142:145], v[220:223], v[10:13]
	v_mfma_f32_16x16x32_bf16 v[26:29], v[142:145], v[182:185], v[26:29]
	v_mfma_f32_16x16x32_bf16 v[26:29], v[138:141], v[178:181], v[26:29]
	v_mfma_f32_16x16x32_bf16 v[42:45], v[138:141], v[170:173], v[42:45]
	v_mfma_f32_16x16x32_bf16 v[42:45], v[142:145], v[174:177], v[42:45]
	v_mfma_f32_16x16x32_bf16 v[58:61], v[142:145], v[166:169], v[58:61]
	v_mfma_f32_16x16x32_bf16 v[58:61], v[138:141], v[162:165], v[58:61]
	v_mfma_f32_16x16x32_bf16 v[46:49], v[154:157], v[162:165], v[46:49]
	v_mfma_f32_16x16x32_bf16 v[46:49], v[158:161], v[166:169], v[46:49]
	v_mfma_f32_16x16x32_bf16 v[30:33], v[158:161], v[174:177], v[30:33]
	v_mfma_f32_16x16x32_bf16 v[30:33], v[154:157], v[170:173], v[30:33]
	v_mfma_f32_16x16x32_bf16 v[14:17], v[154:157], v[178:181], v[14:17]
	v_mfma_f32_16x16x32_bf16 v[14:17], v[158:161], v[182:185], v[14:17]
	v_mfma_f32_16x16x32_bf16 v[2:5], v[158:161], v[220:223], v[2:5]
	v_mfma_f32_16x16x32_bf16 v[2:5], v[154:157], v[186:189], v[2:5]
	v_mfma_f32_16x16x32_bf16 v[6:9], v[146:149], v[186:189], v[6:9]
	v_mfma_f32_16x16x32_bf16 v[6:9], v[150:153], v[220:223], v[6:9]
	v_mfma_f32_16x16x32_bf16 v[22:25], v[150:153], v[182:185], v[22:25]
	v_mfma_f32_16x16x32_bf16 v[22:25], v[146:149], v[178:181], v[22:25]
	v_mfma_f32_16x16x32_bf16 v[38:41], v[146:149], v[170:173], v[38:41]
	v_mfma_f32_16x16x32_bf16 v[38:41], v[150:153], v[174:177], v[38:41]
	v_mfma_f32_16x16x32_bf16 v[54:57], v[150:153], v[166:169], v[54:57]
	v_mfma_f32_16x16x32_bf16 v[54:57], v[146:149], v[162:165], v[54:57]
	s_setprio 0
	s_barrier
	s_add_i32 s70, s70, 2
	s_add_u32 s61, s61, 0x100
	s_addc_u32 s69, s69, 0
	s_cmpk_gt_u32 s70, 0xa9
	s_mov_b64 s[44:45], s[46:47]
	s_cbranch_scc0 .LBB0_983
	s_and_b64 vcc, exec, s[30:31]
	s_cbranch_vccz .LBB0_986
	s_barrier
